# same as previous version with a longer MFMA-result to VALU-read distance at the end of the sgemm_sample K loop
# speedup vs baseline: 1.0380x; 1.0024x over previous
; template <int MODE>
; __device__ __forceinline__ void sgemm_sample(LAS unsigned char* lds, const bf16_t* A, const bf16_t* Bt, int K, const float* resid, float* out, bf16_t* xb, float* ssq_out, const float* ssq_in) {
;     ...
;     for (int uu = u; uu < 2048; uu += gridDim.x * 8) {
;         const int rt = uu >> 6, ct = uu & 63; const int row = NTOKP + rt * 16 + fr, col0 = ct * 16 + fq * 4;
;         const bf16_t* ap = A + (size_t)row * K + fq * 8; const bf16_t* bp = Bt + (size_t)(ct * 16 + fr) * K + fq * 8;
;         f32x4 acc = {0.f, 0.f, 0.f, 0.f};
; #pragma unroll 8
;         for (int ks = 0; ks < K / 32; ++ks) {
;             const bf16x8 a = *(const bf16x8*)(ap + ks * 32); const bf16x8 b = *(const bf16x8*)(bp + ks * 32);
;             acc = __builtin_amdgcn_mfma_f32_16x16x32_bf16(b, a, acc, 0, 0, 0);
;         }
;         if (MODE == 0) {
;             const f32x4 x = *(const f32x4*)(resid + (size_t)(row - NTOKP) * D + col0) + acc;
.LBB0_894:
	s_and_b32 s6, s15, 63
	v_lshl_or_b32 v4, s6, 15, v21
	s_ashr_i32 s6, s3, 2
	s_and_b32 s6, s6, -16
	s_add_i32 s6, s6, 0x8000
	v_or_b32_e32 v12, s6, v17
	v_ashrrev_i32_e32 v13, 31, v12
	v_lshlrev_b64 v[8:9], 11, v[12:13]
	v_lshl_add_u64 v[10:11], v[6:7], 0, v[4:5]
	v_lshl_add_u64 v[14:15], v[6:7], 0, v[8:9]
	s_mov_b64 s[16:17], 0
	v_mov_b32_e32 v0, 0
	v_mov_b32_e32 v1, v5
	v_mov_b32_e32 v2, v5
	v_mov_b32_e32 v3, v5
	s_cmpk_lg_i32 s34, 0x100
	s_cbranch_scc1 .LBB0_895
	s_waitcnt vmcnt(0)
	s_and_b32 s18, s3, 63
	v_lshl_or_b32 v24, s18, 4, v18
	v_lshlrev_b64 v[14:15], 12, v[12:13]
	v_lshl_add_u64 v[10:11], s[40:41], 0, v[14:15]
	v_lshlrev_b32_e32 v4, 2, v24
	v_lshl_add_u64 v[10:11], v[10:11], 0, v[4:5]
	v_add_co_u32_e32 v10, vcc, 0xf8000000, v10
	v_lshl_add_u64 v[14:15], s[90:91], 0, v[14:15]
	s_nop 0
	v_addc_co_u32_e32 v11, vcc, -1, v11, vcc
	global_load_dwordx4 v[10:13], v[10:11], off
	s_lshr_b32 s100, s2, 3
	s_lshl_b32 s100, s100, 4
	s_add_i32 s100, s100, 0x8000
	s_mul_i32 s100, s100, 0x800
	s_add_u32 s96, s92, s100
	s_addc_u32 s97, s93, 0
	s_add_u32 s96, s96, 0x15780000
	s_addc_u32 s97, s97, 0
	s_and_b32 s100, s2, 7
	s_lshl_b32 s100, s100, 7
	s_mul_i32 s100, s100, 0x800
	s_add_u32 s98, s92, s100
	s_addc_u32 s99, s93, 0
	s_add_u32 s98, s98, 0x840000
	s_addc_u32 s99, s99, 0
	v_lshrrev_b32_e32 v179, 4, v200
	v_and_b32_e32 v180, 15, v200
	v_and_b32_e32 v181, 15, v179
	v_xor_b32_e32 v180, v180, v181
	v_lshlrev_b32_e32 v180, 4, v180
	s_mov_b32 s100, 0x800
	v_mad_u32_u24 v164, v179, s100, v180
	v_add_u32_e32 v165, 0x10000, v164
	v_add_u32_e32 v166, 0x20000, v164
	v_add_u32_e32 v167, 0x30000, v164
	v_mad_u32_u24 v168, v181, s100, v180
	v_lshlrev_b32_e32 v169, 4, v200
	v_add_u32_e32 v169, 1024, v169
	v_and_b32_e32 v170, 0xff, v200
	v_lshlrev_b32_e32 v170, 4, v170
	v_add_u32_e32 v170, 33792, v170
	v_and_b32_e32 v179, 15, v200
	v_bfe_u32 v180, v200, 4, 2
	v_and_b32_e32 v181, 3, v179
	v_xor_b32_e32 v180, v180, v181
	v_lshlrev_b32_e32 v180, 4, v180
	v_lshrrev_b32_e32 v181, 2, v179
	v_lshl_add_u32 v180, v181, 6, v180
	v_lshl_add_u32 v180, v179, 8, v180
	v_add_u32_e32 v171, 33792, v180
	v_lshrrev_b32_e32 v181, 6, v200
	v_lshlrev_b32_e32 v181, 12, v181
	v_add_u32_e32 v175, v180, v181
	v_add_u32_e32 v175, 1024, v175
	v_xor_b32_e32 v172, 0x40, v171
	v_xor_b32_e32 v176, 0x40, v175
	v_xor_b32_e32 v173, 0x80, v171
	v_xor_b32_e32 v177, 0x80, v175
	v_xor_b32_e32 v174, 0xc0, v171
	v_xor_b32_e32 v178, 0xc0, v175
	global_load_dwordx4 v[64:67], v164, s[98:99]
	global_load_dwordx4 v[68:71], v165, s[98:99]
	global_load_dwordx4 v[72:75], v166, s[98:99]
	global_load_dwordx4 v[76:79], v167, s[98:99]
	global_load_dwordx4 v[80:83], v168, s[96:97]
	s_add_u32 s98, s98, 0x100
	s_addc_u32 s99, s99, 0
	s_add_u32 s96, s96, 0x100
	s_addc_u32 s97, s97, 0
	global_load_dwordx4 v[84:87], v164, s[98:99]
	global_load_dwordx4 v[88:91], v165, s[98:99]
	global_load_dwordx4 v[92:95], v166, s[98:99]
	global_load_dwordx4 v[96:99], v167, s[98:99]
	global_load_dwordx4 v[100:103], v168, s[96:97]
	s_add_u32 s98, s98, 0x100
	s_addc_u32 s99, s99, 0
	s_add_u32 s96, s96, 0x100
	s_addc_u32 s97, s97, 0
	global_load_dwordx4 v[104:107], v164, s[98:99]
	global_load_dwordx4 v[108:111], v165, s[98:99]
	global_load_dwordx4 v[112:115], v166, s[98:99]
	global_load_dwordx4 v[116:119], v167, s[98:99]
	global_load_dwordx4 v[120:123], v168, s[96:97]
	s_add_u32 s98, s98, 0x100
	s_addc_u32 s99, s99, 0
	s_add_u32 s96, s96, 0x100
	s_addc_u32 s97, s97, 0
	global_load_dwordx4 v[124:127], v164, s[98:99]
	global_load_dwordx4 v[128:131], v165, s[98:99]
	global_load_dwordx4 v[132:135], v166, s[98:99]
	global_load_dwordx4 v[136:139], v167, s[98:99]
	global_load_dwordx4 v[140:143], v168, s[96:97]
	s_add_u32 s98, s98, 0x100
	s_addc_u32 s99, s99, 0
	s_add_u32 s96, s96, 0x100
	s_addc_u32 s97, s97, 0
	global_load_dwordx4 v[144:147], v164, s[98:99]
	global_load_dwordx4 v[148:151], v165, s[98:99]
	global_load_dwordx4 v[152:155], v166, s[98:99]
	global_load_dwordx4 v[156:159], v167, s[98:99]
	global_load_dwordx4 v[160:163], v168, s[96:97]
	s_add_u32 s98, s98, 0x100
	s_addc_u32 s99, s99, 0
	s_add_u32 s96, s96, 0x100
	s_addc_u32 s97, s97, 0
	s_waitcnt vmcnt(24)
	ds_write_b128 v169, v[64:67]
	s_waitcnt vmcnt(23)
	ds_write_b128 v169, v[68:71] offset:8192
	s_waitcnt vmcnt(22)
	ds_write_b128 v169, v[72:75] offset:16384
	s_waitcnt vmcnt(21)
	ds_write_b128 v169, v[76:79] offset:24576
	s_waitcnt vmcnt(20)
	ds_write_b128 v170, v[80:83]
	s_waitcnt lgkmcnt(0)
	s_barrier
	s_waitcnt vmcnt(19)
	ds_write_b128 v169, v[84:87] offset:36864
	s_waitcnt vmcnt(18)
	ds_write_b128 v169, v[88:91] offset:45056
	s_waitcnt vmcnt(17)
	ds_write_b128 v169, v[92:95] offset:53248
	s_waitcnt vmcnt(16)
	ds_write_b128 v169, v[96:99] offset:61440
	s_waitcnt vmcnt(15)
	ds_write_b128 v170, v[100:103] offset:36864
	global_load_dwordx4 v[64:67], v164, s[98:99]
	global_load_dwordx4 v[68:71], v165, s[98:99]
	global_load_dwordx4 v[72:75], v166, s[98:99]
	global_load_dwordx4 v[76:79], v167, s[98:99]
	global_load_dwordx4 v[80:83], v168, s[96:97]
	s_add_u32 s98, s98, 0x100
	s_addc_u32 s99, s99, 0
	s_add_u32 s96, s96, 0x100
	s_addc_u32 s97, s97, 0
	ds_read_b128 v[204:207], v175
	ds_read_b128 v[208:211], v171
	ds_read_b128 v[212:215], v176
	ds_read_b128 v[216:219], v172
	ds_read_b128 v[220:223], v177
	ds_read_b128 v[224:227], v173
	ds_read_b128 v[228:231], v178
	ds_read_b128 v[232:235], v174
	s_waitcnt lgkmcnt(6)
	v_mfma_f32_16x16x32_bf16 v[0:3], v[204:207], v[208:211], v[0:3]
	s_waitcnt lgkmcnt(4)
	v_mfma_f32_16x16x32_bf16 v[0:3], v[212:215], v[216:219], v[0:3]
	s_waitcnt lgkmcnt(2)
	v_mfma_f32_16x16x32_bf16 v[0:3], v[220:223], v[224:227], v[0:3]
	s_waitcnt lgkmcnt(0)
	v_mfma_f32_16x16x32_bf16 v[0:3], v[228:231], v[232:235], v[0:3]
	s_waitcnt lgkmcnt(0)
	s_barrier
; template <int MODE>
; __device__ __forceinline__ void sgemm_sample(LAS unsigned char* lds, const bf16_t* A, const bf16_t* Bt, int K, const float* resid, float* out, bf16_t* xb, float* ssq_out, const float* ssq_in) {
;     ...
; #pragma unroll 8
;         for (int ks = 0; ks < K / 32; ++ks) {
;             const bf16x8 a = *(const bf16x8*)(ap + ks * 32); const bf16x8 b = *(const bf16x8*)(bp + ks * 32);
;             acc = __builtin_amdgcn_mfma_f32_16x16x32_bf16(b, a, acc, 0, 0, 0);
;         }
	s_waitcnt vmcnt(19)
	ds_write_b128 v169, v[104:107]
	s_waitcnt vmcnt(18)
	ds_write_b128 v169, v[108:111] offset:8192
	s_waitcnt vmcnt(17)
	ds_write_b128 v169, v[112:115] offset:16384
	s_waitcnt vmcnt(16)
	ds_write_b128 v169, v[116:119] offset:24576
	s_waitcnt vmcnt(15)
	ds_write_b128 v170, v[120:123]
	global_load_dwordx4 v[84:87], v164, s[98:99]
	global_load_dwordx4 v[88:91], v165, s[98:99]
	global_load_dwordx4 v[92:95], v166, s[98:99]
	global_load_dwordx4 v[96:99], v167, s[98:99]
	global_load_dwordx4 v[100:103], v168, s[96:97]
	s_add_u32 s98, s98, 0x100
	s_addc_u32 s99, s99, 0
	s_add_u32 s96, s96, 0x100
	s_addc_u32 s97, s97, 0
	ds_read_b128 v[204:207], v175 offset:36864
	ds_read_b128 v[208:211], v171 offset:36864
	ds_read_b128 v[212:215], v176 offset:36864
	ds_read_b128 v[216:219], v172 offset:36864
	ds_read_b128 v[220:223], v177 offset:36864
	ds_read_b128 v[224:227], v173 offset:36864
	ds_read_b128 v[228:231], v178 offset:36864
	ds_read_b128 v[232:235], v174 offset:36864
	s_waitcnt lgkmcnt(6)
	v_mfma_f32_16x16x32_bf16 v[0:3], v[204:207], v[208:211], v[0:3]
	s_waitcnt lgkmcnt(4)
	v_mfma_f32_16x16x32_bf16 v[0:3], v[212:215], v[216:219], v[0:3]
	s_waitcnt lgkmcnt(2)
	v_mfma_f32_16x16x32_bf16 v[0:3], v[220:223], v[224:227], v[0:3]
	s_waitcnt lgkmcnt(0)
	v_mfma_f32_16x16x32_bf16 v[0:3], v[228:231], v[232:235], v[0:3]
	s_waitcnt lgkmcnt(0)
	s_barrier
	s_waitcnt vmcnt(19)
	ds_write_b128 v169, v[124:127] offset:36864
	s_waitcnt vmcnt(18)
	ds_write_b128 v169, v[128:131] offset:45056
	s_waitcnt vmcnt(17)
	ds_write_b128 v169, v[132:135] offset:53248
	s_waitcnt vmcnt(16)
	ds_write_b128 v169, v[136:139] offset:61440
	s_waitcnt vmcnt(15)
	ds_write_b128 v170, v[140:143] offset:36864
	global_load_dwordx4 v[104:107], v164, s[98:99]
	global_load_dwordx4 v[108:111], v165, s[98:99]
	global_load_dwordx4 v[112:115], v166, s[98:99]
	global_load_dwordx4 v[116:119], v167, s[98:99]
	global_load_dwordx4 v[120:123], v168, s[96:97]
	s_add_u32 s98, s98, 0x100
	s_addc_u32 s99, s99, 0
	s_add_u32 s96, s96, 0x100
	s_addc_u32 s97, s97, 0
	ds_read_b128 v[204:207], v175
	ds_read_b128 v[208:211], v171
	ds_read_b128 v[212:215], v176
	ds_read_b128 v[216:219], v172
	ds_read_b128 v[220:223], v177
	ds_read_b128 v[224:227], v173
	ds_read_b128 v[228:231], v178
	ds_read_b128 v[232:235], v174
	s_waitcnt lgkmcnt(6)
	v_mfma_f32_16x16x32_bf16 v[0:3], v[204:207], v[208:211], v[0:3]
	s_waitcnt lgkmcnt(4)
	v_mfma_f32_16x16x32_bf16 v[0:3], v[212:215], v[216:219], v[0:3]
	s_waitcnt lgkmcnt(2)
	v_mfma_f32_16x16x32_bf16 v[0:3], v[220:223], v[224:227], v[0:3]
	s_waitcnt lgkmcnt(0)
	v_mfma_f32_16x16x32_bf16 v[0:3], v[228:231], v[232:235], v[0:3]
	s_waitcnt lgkmcnt(0)
	s_barrier
	s_waitcnt vmcnt(19)
	ds_write_b128 v169, v[144:147]
	s_waitcnt vmcnt(18)
	ds_write_b128 v169, v[148:151] offset:8192
	s_waitcnt vmcnt(17)
	ds_write_b128 v169, v[152:155] offset:16384
	s_waitcnt vmcnt(16)
	ds_write_b128 v169, v[156:159] offset:24576
	s_waitcnt vmcnt(15)
	ds_write_b128 v170, v[160:163]
	ds_read_b128 v[204:207], v175 offset:36864
	ds_read_b128 v[208:211], v171 offset:36864
	ds_read_b128 v[212:215], v176 offset:36864
	ds_read_b128 v[216:219], v172 offset:36864
	ds_read_b128 v[220:223], v177 offset:36864
	ds_read_b128 v[224:227], v173 offset:36864
	ds_read_b128 v[228:231], v178 offset:36864
	ds_read_b128 v[232:235], v174 offset:36864
	s_waitcnt lgkmcnt(6)
	v_mfma_f32_16x16x32_bf16 v[0:3], v[204:207], v[208:211], v[0:3]
	s_waitcnt lgkmcnt(4)
	v_mfma_f32_16x16x32_bf16 v[0:3], v[212:215], v[216:219], v[0:3]
	s_waitcnt lgkmcnt(2)
	v_mfma_f32_16x16x32_bf16 v[0:3], v[220:223], v[224:227], v[0:3]
	s_waitcnt lgkmcnt(0)
	v_mfma_f32_16x16x32_bf16 v[0:3], v[228:231], v[232:235], v[0:3]
	s_waitcnt lgkmcnt(0)
	s_barrier
; template <int MODE>
; __device__ __forceinline__ void sgemm_sample(LAS unsigned char* lds, const bf16_t* A, const bf16_t* Bt, int K, const float* resid, float* out, bf16_t* xb, float* ssq_out, const float* ssq_in) {
;     ...
; #pragma unroll 8
;         for (int ks = 0; ks < K / 32; ++ks) {
;             const bf16x8 a = *(const bf16x8*)(ap + ks * 32); const bf16x8 b = *(const bf16x8*)(bp + ks * 32);
;             acc = __builtin_amdgcn_mfma_f32_16x16x32_bf16(b, a, acc, 0, 0, 0);
;         }
	s_waitcnt vmcnt(14)
	ds_write_b128 v169, v[64:67] offset:36864
	s_waitcnt vmcnt(13)
	ds_write_b128 v169, v[68:71] offset:45056
	s_waitcnt vmcnt(12)
	ds_write_b128 v169, v[72:75] offset:53248
	s_waitcnt vmcnt(11)
	ds_write_b128 v169, v[76:79] offset:61440
	s_waitcnt vmcnt(10)
	ds_write_b128 v170, v[80:83] offset:36864
	ds_read_b128 v[204:207], v175
	ds_read_b128 v[208:211], v171
	ds_read_b128 v[212:215], v176
	ds_read_b128 v[216:219], v172
	ds_read_b128 v[220:223], v177
	ds_read_b128 v[224:227], v173
	ds_read_b128 v[228:231], v178
	ds_read_b128 v[232:235], v174
	s_waitcnt lgkmcnt(6)
	v_mfma_f32_16x16x32_bf16 v[0:3], v[204:207], v[208:211], v[0:3]
	s_waitcnt lgkmcnt(4)
	v_mfma_f32_16x16x32_bf16 v[0:3], v[212:215], v[216:219], v[0:3]
	s_waitcnt lgkmcnt(2)
	v_mfma_f32_16x16x32_bf16 v[0:3], v[220:223], v[224:227], v[0:3]
	s_waitcnt lgkmcnt(0)
	v_mfma_f32_16x16x32_bf16 v[0:3], v[228:231], v[232:235], v[0:3]
	s_waitcnt lgkmcnt(0)
	s_barrier
	s_waitcnt vmcnt(9)
	ds_write_b128 v169, v[84:87]
	s_waitcnt vmcnt(8)
	ds_write_b128 v169, v[88:91] offset:8192
	s_waitcnt vmcnt(7)
	ds_write_b128 v169, v[92:95] offset:16384
	s_waitcnt vmcnt(6)
	ds_write_b128 v169, v[96:99] offset:24576
	s_waitcnt vmcnt(5)
	ds_write_b128 v170, v[100:103]
	ds_read_b128 v[204:207], v175 offset:36864
	ds_read_b128 v[208:211], v171 offset:36864
	ds_read_b128 v[212:215], v176 offset:36864
	ds_read_b128 v[216:219], v172 offset:36864
	ds_read_b128 v[220:223], v177 offset:36864
	ds_read_b128 v[224:227], v173 offset:36864
	ds_read_b128 v[228:231], v178 offset:36864
	ds_read_b128 v[232:235], v174 offset:36864
	s_waitcnt lgkmcnt(6)
	v_mfma_f32_16x16x32_bf16 v[0:3], v[204:207], v[208:211], v[0:3]
	s_waitcnt lgkmcnt(4)
	v_mfma_f32_16x16x32_bf16 v[0:3], v[212:215], v[216:219], v[0:3]
	s_waitcnt lgkmcnt(2)
	v_mfma_f32_16x16x32_bf16 v[0:3], v[220:223], v[224:227], v[0:3]
	s_waitcnt lgkmcnt(0)
	v_mfma_f32_16x16x32_bf16 v[0:3], v[228:231], v[232:235], v[0:3]
	s_waitcnt lgkmcnt(0)
	s_barrier
	s_waitcnt vmcnt(4)
	ds_write_b128 v169, v[104:107] offset:36864
	s_waitcnt vmcnt(3)
	ds_write_b128 v169, v[108:111] offset:45056
	s_waitcnt vmcnt(2)
	ds_write_b128 v169, v[112:115] offset:53248
	s_waitcnt vmcnt(1)
	ds_write_b128 v169, v[116:119] offset:61440
	s_waitcnt vmcnt(0)
	ds_write_b128 v170, v[120:123] offset:36864
	ds_read_b128 v[204:207], v175
	ds_read_b128 v[208:211], v171
	ds_read_b128 v[212:215], v176
	ds_read_b128 v[216:219], v172
	ds_read_b128 v[220:223], v177
	ds_read_b128 v[224:227], v173
	ds_read_b128 v[228:231], v178
	ds_read_b128 v[232:235], v174
	s_waitcnt lgkmcnt(6)
	v_mfma_f32_16x16x32_bf16 v[0:3], v[204:207], v[208:211], v[0:3]
	s_waitcnt lgkmcnt(4)
	v_mfma_f32_16x16x32_bf16 v[0:3], v[212:215], v[216:219], v[0:3]
	s_waitcnt lgkmcnt(2)
	v_mfma_f32_16x16x32_bf16 v[0:3], v[220:223], v[224:227], v[0:3]
	s_waitcnt lgkmcnt(0)
	v_mfma_f32_16x16x32_bf16 v[0:3], v[228:231], v[232:235], v[0:3]
	s_waitcnt lgkmcnt(0)
	s_barrier
	ds_read_b128 v[204:207], v175 offset:36864
	ds_read_b128 v[208:211], v171 offset:36864
	ds_read_b128 v[212:215], v176 offset:36864
	ds_read_b128 v[216:219], v172 offset:36864
	ds_read_b128 v[220:223], v177 offset:36864
	ds_read_b128 v[224:227], v173 offset:36864
	ds_read_b128 v[228:231], v178 offset:36864
	ds_read_b128 v[232:235], v174 offset:36864
	s_waitcnt lgkmcnt(6)
	v_mfma_f32_16x16x32_bf16 v[0:3], v[204:207], v[208:211], v[0:3]
	s_waitcnt lgkmcnt(4)
	v_mfma_f32_16x16x32_bf16 v[0:3], v[212:215], v[216:219], v[0:3]
	s_waitcnt lgkmcnt(2)
	v_mfma_f32_16x16x32_bf16 v[0:3], v[220:223], v[224:227], v[0:3]
	s_waitcnt lgkmcnt(0)
	v_mfma_f32_16x16x32_bf16 v[0:3], v[228:231], v[232:235], v[0:3]
	s_nop 7
	s_nop 7
	s_nop 3
	s_branch .Lsgx0_done

; template <int MODE>
; __device__ __forceinline__ void sgemm_sample(LAS unsigned char* lds, const bf16_t* A, const bf16_t* Bt, int K, const float* resid, float* out, bf16_t* xb, float* ssq_out, const float* ssq_in) {
;     ...
;     for (int uu = u; uu < 2048; uu += gridDim.x * 8) {
;         const int rt = uu >> 6, ct = uu & 63; const int row = NTOKP + rt * 16 + fr, col0 = ct * 16 + fq * 4;
;         const bf16_t* ap = A + (size_t)row * K + fq * 8; const bf16_t* bp = Bt + (size_t)(ct * 16 + fr) * K + fq * 8;
;         f32x4 acc = {0.f, 0.f, 0.f, 0.f};
; #pragma unroll 8
;         for (int ks = 0; ks < K / 32; ++ks) {
;             const bf16x8 a = *(const bf16x8*)(ap + ks * 32); const bf16x8 b = *(const bf16x8*)(bp + ks * 32);
;             acc = __builtin_amdgcn_mfma_f32_16x16x32_bf16(b, a, acc, 0, 0, 0);
;         }
;     ...
;             const float sc = rs_from_parts(ssq_in + (size_t)row * 16) * 0.0625f;
.LBB0_999:
	s_lshl_b32 s0, s7, 11
	s_and_b32 s0, s0, 0x1f8000
	v_lshl_or_b32 v4, v18, 1, s0
	s_ashr_i32 s0, s3, 2
	s_and_b32 s0, s0, -16
	v_add_u32_e32 v10, s0, v16
	v_ashrrev_i32_e32 v11, 31, v10
	v_lshlrev_b64 v[8:9], 11, v[10:11]
	v_lshl_add_u64 v[12:13], v[6:7], 0, v[4:5]
	v_lshl_add_u64 v[14:15], v[6:7], 0, v[8:9]
	s_mov_b64 s[0:1], 0
	v_mov_b32_e32 v0, 0
	v_mov_b32_e32 v1, v5
	v_mov_b32_e32 v2, v5
	v_mov_b32_e32 v3, v5
	s_cmpk_lg_i32 s34, 0x100
	s_cbranch_scc1 .LBB0_1000
	s_waitcnt vmcnt(0)
	v_lshlrev_b64 v[10:11], 6, v[10:11]
	v_lshl_add_u64 v[14:15], s[4:5], 0, v[10:11]
	global_load_dwordx4 v[10:13], v[14:15], off
	global_load_dwordx4 v[20:23], v[14:15], off offset:16
	global_load_dwordx4 v[24:27], v[14:15], off offset:32
	global_load_dwordx4 v[28:31], v[14:15], off offset:48
	s_lshr_b32 s100, s2, 3
	s_lshl_b32 s100, s100, 4
	s_add_i32 s100, s100, 0x8000
	s_mul_i32 s100, s100, 0x800
	s_add_u32 s96, s92, s100
	s_addc_u32 s97, s93, 0
	s_add_u32 s96, s96, 0xa4c0000
	s_addc_u32 s97, s97, 0
	s_and_b32 s100, s2, 7
	s_lshl_b32 s100, s100, 7
	s_mul_i32 s100, s100, 0x800
	s_add_u32 s98, s92, s100
	s_addc_u32 s99, s93, 0
	s_add_u32 s98, s98, 0xa40000
	s_addc_u32 s99, s99, 0
	v_lshrrev_b32_e32 v179, 4, v200
	v_and_b32_e32 v180, 15, v200
	v_and_b32_e32 v181, 15, v179
	v_xor_b32_e32 v180, v180, v181
	v_lshlrev_b32_e32 v180, 4, v180
	s_mov_b32 s100, 0x800
	v_mad_u32_u24 v164, v179, s100, v180
	v_add_u32_e32 v165, 0x10000, v164
	v_add_u32_e32 v166, 0x20000, v164
	v_add_u32_e32 v167, 0x30000, v164
	v_mad_u32_u24 v168, v181, s100, v180
	v_lshlrev_b32_e32 v169, 4, v200
	v_add_u32_e32 v169, 1024, v169
	v_and_b32_e32 v170, 0xff, v200
	v_lshlrev_b32_e32 v170, 4, v170
	v_add_u32_e32 v170, 33792, v170
	v_and_b32_e32 v179, 15, v200
	v_bfe_u32 v180, v200, 4, 2
	v_and_b32_e32 v181, 3, v179
	v_xor_b32_e32 v180, v180, v181
	v_lshlrev_b32_e32 v180, 4, v180
	v_lshrrev_b32_e32 v181, 2, v179
	v_lshl_add_u32 v180, v181, 6, v180
	v_lshl_add_u32 v180, v179, 8, v180
	v_add_u32_e32 v171, 33792, v180
	v_lshrrev_b32_e32 v181, 6, v200
	v_lshlrev_b32_e32 v181, 12, v181
	v_add_u32_e32 v175, v180, v181
	v_add_u32_e32 v175, 1024, v175
	v_xor_b32_e32 v172, 0x40, v171
	v_xor_b32_e32 v176, 0x40, v175
	v_xor_b32_e32 v173, 0x80, v171
	v_xor_b32_e32 v177, 0x80, v175
	v_xor_b32_e32 v174, 0xc0, v171
	v_xor_b32_e32 v178, 0xc0, v175
	global_load_dwordx4 v[64:67], v164, s[98:99]
	global_load_dwordx4 v[68:71], v165, s[98:99]
	global_load_dwordx4 v[72:75], v166, s[98:99]
	global_load_dwordx4 v[76:79], v167, s[98:99]
	global_load_dwordx4 v[80:83], v168, s[96:97]
	s_add_u32 s98, s98, 0x100
	s_addc_u32 s99, s99, 0
	s_add_u32 s96, s96, 0x100
	s_addc_u32 s97, s97, 0
	global_load_dwordx4 v[84:87], v164, s[98:99]
	global_load_dwordx4 v[88:91], v165, s[98:99]
	global_load_dwordx4 v[92:95], v166, s[98:99]
	global_load_dwordx4 v[96:99], v167, s[98:99]
	global_load_dwordx4 v[100:103], v168, s[96:97]
	s_add_u32 s98, s98, 0x100
	s_addc_u32 s99, s99, 0
	s_add_u32 s96, s96, 0x100
	s_addc_u32 s97, s97, 0
	global_load_dwordx4 v[104:107], v164, s[98:99]
	global_load_dwordx4 v[108:111], v165, s[98:99]
	global_load_dwordx4 v[112:115], v166, s[98:99]
	global_load_dwordx4 v[116:119], v167, s[98:99]
	global_load_dwordx4 v[120:123], v168, s[96:97]
	s_add_u32 s98, s98, 0x100
	s_addc_u32 s99, s99, 0
	s_add_u32 s96, s96, 0x100
	s_addc_u32 s97, s97, 0
	global_load_dwordx4 v[124:127], v164, s[98:99]
	global_load_dwordx4 v[128:131], v165, s[98:99]
	global_load_dwordx4 v[132:135], v166, s[98:99]
	global_load_dwordx4 v[136:139], v167, s[98:99]
	global_load_dwordx4 v[140:143], v168, s[96:97]
	s_add_u32 s98, s98, 0x100
	s_addc_u32 s99, s99, 0
	s_add_u32 s96, s96, 0x100
	s_addc_u32 s97, s97, 0
	global_load_dwordx4 v[144:147], v164, s[98:99]
	global_load_dwordx4 v[148:151], v165, s[98:99]
	global_load_dwordx4 v[152:155], v166, s[98:99]
	global_load_dwordx4 v[156:159], v167, s[98:99]
	global_load_dwordx4 v[160:163], v168, s[96:97]
	s_add_u32 s98, s98, 0x100
	s_addc_u32 s99, s99, 0
	s_add_u32 s96, s96, 0x100
	s_addc_u32 s97, s97, 0
	s_waitcnt vmcnt(24)
	ds_write_b128 v169, v[64:67]
	s_waitcnt vmcnt(23)
	ds_write_b128 v169, v[68:71] offset:8192
	s_waitcnt vmcnt(22)
	ds_write_b128 v169, v[72:75] offset:16384
	s_waitcnt vmcnt(21)
	ds_write_b128 v169, v[76:79] offset:24576
	s_waitcnt vmcnt(20)
	ds_write_b128 v170, v[80:83]
	s_waitcnt lgkmcnt(0)
	s_barrier
	s_waitcnt vmcnt(19)
	ds_write_b128 v169, v[84:87] offset:36864
	s_waitcnt vmcnt(18)
	ds_write_b128 v169, v[88:91] offset:45056
	s_waitcnt vmcnt(17)
	ds_write_b128 v169, v[92:95] offset:53248
	s_waitcnt vmcnt(16)
	ds_write_b128 v169, v[96:99] offset:61440
	s_waitcnt vmcnt(15)
	ds_write_b128 v170, v[100:103] offset:36864
	global_load_dwordx4 v[64:67], v164, s[98:99]
	global_load_dwordx4 v[68:71], v165, s[98:99]
	global_load_dwordx4 v[72:75], v166, s[98:99]
	global_load_dwordx4 v[76:79], v167, s[98:99]
	global_load_dwordx4 v[80:83], v168, s[96:97]
	s_add_u32 s98, s98, 0x100
	s_addc_u32 s99, s99, 0
	s_add_u32 s96, s96, 0x100
	s_addc_u32 s97, s97, 0
	ds_read_b128 v[204:207], v175
	ds_read_b128 v[208:211], v171
	ds_read_b128 v[212:215], v176
	ds_read_b128 v[216:219], v172
	ds_read_b128 v[220:223], v177
	ds_read_b128 v[224:227], v173
	ds_read_b128 v[228:231], v178
	ds_read_b128 v[232:235], v174
	s_waitcnt lgkmcnt(6)
	v_mfma_f32_16x16x32_bf16 v[0:3], v[204:207], v[208:211], v[0:3]
	s_waitcnt lgkmcnt(4)
	v_mfma_f32_16x16x32_bf16 v[0:3], v[212:215], v[216:219], v[0:3]
	s_waitcnt lgkmcnt(2)
	v_mfma_f32_16x16x32_bf16 v[0:3], v[220:223], v[224:227], v[0:3]
	s_waitcnt lgkmcnt(0)
	v_mfma_f32_16x16x32_bf16 v[0:3], v[228:231], v[232:235], v[0:3]
	s_waitcnt lgkmcnt(0)
	s_barrier
; template <int MODE>
; __device__ __forceinline__ void sgemm_sample(LAS unsigned char* lds, const bf16_t* A, const bf16_t* Bt, int K, const float* resid, float* out, bf16_t* xb, float* ssq_out, const float* ssq_in) {
;     ...
; #pragma unroll 8
;         for (int ks = 0; ks < K / 32; ++ks) {
;             const bf16x8 a = *(const bf16x8*)(ap + ks * 32); const bf16x8 b = *(const bf16x8*)(bp + ks * 32);
;             acc = __builtin_amdgcn_mfma_f32_16x16x32_bf16(b, a, acc, 0, 0, 0);
;         }
	s_waitcnt vmcnt(19)
	ds_write_b128 v169, v[104:107]
	s_waitcnt vmcnt(18)
	ds_write_b128 v169, v[108:111] offset:8192
	s_waitcnt vmcnt(17)
	ds_write_b128 v169, v[112:115] offset:16384
	s_waitcnt vmcnt(16)
	ds_write_b128 v169, v[116:119] offset:24576
	s_waitcnt vmcnt(15)
	ds_write_b128 v170, v[120:123]
	global_load_dwordx4 v[84:87], v164, s[98:99]
	global_load_dwordx4 v[88:91], v165, s[98:99]
	global_load_dwordx4 v[92:95], v166, s[98:99]
	global_load_dwordx4 v[96:99], v167, s[98:99]
	global_load_dwordx4 v[100:103], v168, s[96:97]
	s_add_u32 s98, s98, 0x100
	s_addc_u32 s99, s99, 0
	s_add_u32 s96, s96, 0x100
	s_addc_u32 s97, s97, 0
	ds_read_b128 v[204:207], v175 offset:36864
	ds_read_b128 v[208:211], v171 offset:36864
	ds_read_b128 v[212:215], v176 offset:36864
	ds_read_b128 v[216:219], v172 offset:36864
	ds_read_b128 v[220:223], v177 offset:36864
	ds_read_b128 v[224:227], v173 offset:36864
	ds_read_b128 v[228:231], v178 offset:36864
	ds_read_b128 v[232:235], v174 offset:36864
	s_waitcnt lgkmcnt(6)
	v_mfma_f32_16x16x32_bf16 v[0:3], v[204:207], v[208:211], v[0:3]
	s_waitcnt lgkmcnt(4)
	v_mfma_f32_16x16x32_bf16 v[0:3], v[212:215], v[216:219], v[0:3]
	s_waitcnt lgkmcnt(2)
	v_mfma_f32_16x16x32_bf16 v[0:3], v[220:223], v[224:227], v[0:3]
	s_waitcnt lgkmcnt(0)
	v_mfma_f32_16x16x32_bf16 v[0:3], v[228:231], v[232:235], v[0:3]
	s_waitcnt lgkmcnt(0)
	s_barrier
	s_waitcnt vmcnt(19)
	ds_write_b128 v169, v[124:127] offset:36864
	s_waitcnt vmcnt(18)
	ds_write_b128 v169, v[128:131] offset:45056
	s_waitcnt vmcnt(17)
	ds_write_b128 v169, v[132:135] offset:53248
	s_waitcnt vmcnt(16)
	ds_write_b128 v169, v[136:139] offset:61440
	s_waitcnt vmcnt(15)
	ds_write_b128 v170, v[140:143] offset:36864
	global_load_dwordx4 v[104:107], v164, s[98:99]
	global_load_dwordx4 v[108:111], v165, s[98:99]
	global_load_dwordx4 v[112:115], v166, s[98:99]
	global_load_dwordx4 v[116:119], v167, s[98:99]
	global_load_dwordx4 v[120:123], v168, s[96:97]
	s_add_u32 s98, s98, 0x100
	s_addc_u32 s99, s99, 0
	s_add_u32 s96, s96, 0x100
	s_addc_u32 s97, s97, 0
	ds_read_b128 v[204:207], v175
	ds_read_b128 v[208:211], v171
	ds_read_b128 v[212:215], v176
	ds_read_b128 v[216:219], v172
	ds_read_b128 v[220:223], v177
	ds_read_b128 v[224:227], v173
	ds_read_b128 v[228:231], v178
	ds_read_b128 v[232:235], v174
	s_waitcnt lgkmcnt(6)
	v_mfma_f32_16x16x32_bf16 v[0:3], v[204:207], v[208:211], v[0:3]
	s_waitcnt lgkmcnt(4)
	v_mfma_f32_16x16x32_bf16 v[0:3], v[212:215], v[216:219], v[0:3]
	s_waitcnt lgkmcnt(2)
	v_mfma_f32_16x16x32_bf16 v[0:3], v[220:223], v[224:227], v[0:3]
	s_waitcnt lgkmcnt(0)
	v_mfma_f32_16x16x32_bf16 v[0:3], v[228:231], v[232:235], v[0:3]
	s_waitcnt lgkmcnt(0)
	s_barrier
	s_waitcnt vmcnt(19)
	ds_write_b128 v169, v[144:147]
	s_waitcnt vmcnt(18)
	ds_write_b128 v169, v[148:151] offset:8192
	s_waitcnt vmcnt(17)
	ds_write_b128 v169, v[152:155] offset:16384
	s_waitcnt vmcnt(16)
	ds_write_b128 v169, v[156:159] offset:24576
	s_waitcnt vmcnt(15)
	ds_write_b128 v170, v[160:163]
	ds_read_b128 v[204:207], v175 offset:36864
	ds_read_b128 v[208:211], v171 offset:36864
	ds_read_b128 v[212:215], v176 offset:36864
	ds_read_b128 v[216:219], v172 offset:36864
	ds_read_b128 v[220:223], v177 offset:36864
	ds_read_b128 v[224:227], v173 offset:36864
	ds_read_b128 v[228:231], v178 offset:36864
	ds_read_b128 v[232:235], v174 offset:36864
	s_waitcnt lgkmcnt(6)
	v_mfma_f32_16x16x32_bf16 v[0:3], v[204:207], v[208:211], v[0:3]
	s_waitcnt lgkmcnt(4)
	v_mfma_f32_16x16x32_bf16 v[0:3], v[212:215], v[216:219], v[0:3]
	s_waitcnt lgkmcnt(2)
	v_mfma_f32_16x16x32_bf16 v[0:3], v[220:223], v[224:227], v[0:3]
	s_waitcnt lgkmcnt(0)
	v_mfma_f32_16x16x32_bf16 v[0:3], v[228:231], v[232:235], v[0:3]
	s_waitcnt lgkmcnt(0)
	s_barrier
; template <int MODE>
; __device__ __forceinline__ void sgemm_sample(LAS unsigned char* lds, const bf16_t* A, const bf16_t* Bt, int K, const float* resid, float* out, bf16_t* xb, float* ssq_out, const float* ssq_in) {
;     ...
; #pragma unroll 8
;         for (int ks = 0; ks < K / 32; ++ks) {
;             const bf16x8 a = *(const bf16x8*)(ap + ks * 32); const bf16x8 b = *(const bf16x8*)(bp + ks * 32);
;             acc = __builtin_amdgcn_mfma_f32_16x16x32_bf16(b, a, acc, 0, 0, 0);
;         }
	s_waitcnt vmcnt(14)
	ds_write_b128 v169, v[64:67] offset:36864
	s_waitcnt vmcnt(13)
	ds_write_b128 v169, v[68:71] offset:45056
	s_waitcnt vmcnt(12)
	ds_write_b128 v169, v[72:75] offset:53248
	s_waitcnt vmcnt(11)
	ds_write_b128 v169, v[76:79] offset:61440
	s_waitcnt vmcnt(10)
	ds_write_b128 v170, v[80:83] offset:36864
	ds_read_b128 v[204:207], v175
	ds_read_b128 v[208:211], v171
	ds_read_b128 v[212:215], v176
	ds_read_b128 v[216:219], v172
	ds_read_b128 v[220:223], v177
	ds_read_b128 v[224:227], v173
	ds_read_b128 v[228:231], v178
	ds_read_b128 v[232:235], v174
	s_waitcnt lgkmcnt(6)
	v_mfma_f32_16x16x32_bf16 v[0:3], v[204:207], v[208:211], v[0:3]
	s_waitcnt lgkmcnt(4)
	v_mfma_f32_16x16x32_bf16 v[0:3], v[212:215], v[216:219], v[0:3]
	s_waitcnt lgkmcnt(2)
	v_mfma_f32_16x16x32_bf16 v[0:3], v[220:223], v[224:227], v[0:3]
	s_waitcnt lgkmcnt(0)
	v_mfma_f32_16x16x32_bf16 v[0:3], v[228:231], v[232:235], v[0:3]
	s_waitcnt lgkmcnt(0)
	s_barrier
	s_waitcnt vmcnt(9)
	ds_write_b128 v169, v[84:87]
	s_waitcnt vmcnt(8)
	ds_write_b128 v169, v[88:91] offset:8192
	s_waitcnt vmcnt(7)
	ds_write_b128 v169, v[92:95] offset:16384
	s_waitcnt vmcnt(6)
	ds_write_b128 v169, v[96:99] offset:24576
	s_waitcnt vmcnt(5)
	ds_write_b128 v170, v[100:103]
	ds_read_b128 v[204:207], v175 offset:36864
	ds_read_b128 v[208:211], v171 offset:36864
	ds_read_b128 v[212:215], v176 offset:36864
	ds_read_b128 v[216:219], v172 offset:36864
	ds_read_b128 v[220:223], v177 offset:36864
	ds_read_b128 v[224:227], v173 offset:36864
	ds_read_b128 v[228:231], v178 offset:36864
	ds_read_b128 v[232:235], v174 offset:36864
	s_waitcnt lgkmcnt(6)
	v_mfma_f32_16x16x32_bf16 v[0:3], v[204:207], v[208:211], v[0:3]
	s_waitcnt lgkmcnt(4)
	v_mfma_f32_16x16x32_bf16 v[0:3], v[212:215], v[216:219], v[0:3]
	s_waitcnt lgkmcnt(2)
	v_mfma_f32_16x16x32_bf16 v[0:3], v[220:223], v[224:227], v[0:3]
	s_waitcnt lgkmcnt(0)
	v_mfma_f32_16x16x32_bf16 v[0:3], v[228:231], v[232:235], v[0:3]
	s_waitcnt lgkmcnt(0)
	s_barrier
	s_waitcnt vmcnt(4)
	ds_write_b128 v169, v[104:107] offset:36864
	s_waitcnt vmcnt(3)
	ds_write_b128 v169, v[108:111] offset:45056
	s_waitcnt vmcnt(2)
	ds_write_b128 v169, v[112:115] offset:53248
	s_waitcnt vmcnt(1)
	ds_write_b128 v169, v[116:119] offset:61440
	s_waitcnt vmcnt(0)
	ds_write_b128 v170, v[120:123] offset:36864
	ds_read_b128 v[204:207], v175
	ds_read_b128 v[208:211], v171
	ds_read_b128 v[212:215], v176
	ds_read_b128 v[216:219], v172
	ds_read_b128 v[220:223], v177
	ds_read_b128 v[224:227], v173
	ds_read_b128 v[228:231], v178
	ds_read_b128 v[232:235], v174
	s_waitcnt lgkmcnt(6)
	v_mfma_f32_16x16x32_bf16 v[0:3], v[204:207], v[208:211], v[0:3]
	s_waitcnt lgkmcnt(4)
	v_mfma_f32_16x16x32_bf16 v[0:3], v[212:215], v[216:219], v[0:3]
	s_waitcnt lgkmcnt(2)
	v_mfma_f32_16x16x32_bf16 v[0:3], v[220:223], v[224:227], v[0:3]
	s_waitcnt lgkmcnt(0)
	v_mfma_f32_16x16x32_bf16 v[0:3], v[228:231], v[232:235], v[0:3]
	s_waitcnt lgkmcnt(0)
	s_barrier
	ds_read_b128 v[204:207], v175 offset:36864
	ds_read_b128 v[208:211], v171 offset:36864
	ds_read_b128 v[212:215], v176 offset:36864
	ds_read_b128 v[216:219], v172 offset:36864
	ds_read_b128 v[220:223], v177 offset:36864
	ds_read_b128 v[224:227], v173 offset:36864
	ds_read_b128 v[228:231], v178 offset:36864
	ds_read_b128 v[232:235], v174 offset:36864
	s_waitcnt lgkmcnt(6)
	v_mfma_f32_16x16x32_bf16 v[0:3], v[204:207], v[208:211], v[0:3]
	s_waitcnt lgkmcnt(4)
	v_mfma_f32_16x16x32_bf16 v[0:3], v[212:215], v[216:219], v[0:3]
	s_waitcnt lgkmcnt(2)
	v_mfma_f32_16x16x32_bf16 v[0:3], v[220:223], v[224:227], v[0:3]
	s_waitcnt lgkmcnt(0)
	v_mfma_f32_16x16x32_bf16 v[0:3], v[228:231], v[232:235], v[0:3]
	s_nop 7
	s_nop 7
	s_nop 3
	s_branch .Lsgx1_done

; template <int MODE>
; __device__ __forceinline__ void sgemm_sample(LAS unsigned char* lds, const bf16_t* A, const bf16_t* Bt, int K, const float* resid, float* out, bf16_t* xb, float* ssq_out, const float* ssq_in) {
;     ...
;     for (int uu = u; uu < 2048; uu += gridDim.x * 8) {
;         const int rt = uu >> 6, ct = uu & 63; const int row = NTOKP + rt * 16 + fr, col0 = ct * 16 + fq * 4;
;         const bf16_t* ap = A + (size_t)row * K + fq * 8; const bf16_t* bp = Bt + (size_t)(ct * 16 + fr) * K + fq * 8;
;         f32x4 acc = {0.f, 0.f, 0.f, 0.f};
; #pragma unroll 8
;         for (int ks = 0; ks < K / 32; ++ks) {
;             const bf16x8 a = *(const bf16x8*)(ap + ks * 32); const bf16x8 b = *(const bf16x8*)(bp + ks * 32);
;             acc = __builtin_amdgcn_mfma_f32_16x16x32_bf16(b, a, acc, 0, 0, 0);
;         }
;         if (MODE == 0) {
;             const f32x4 x = *(const f32x4*)(resid + (size_t)(row - NTOKP) * D + col0) + acc;
.LBB0_1168:
	s_and_b32 s6, s15, 63
	v_lshl_or_b32 v4, s6, 15, v21
	s_ashr_i32 s6, s3, 2
	s_and_b32 s6, s6, -16
	s_add_i32 s6, s6, 0x8000
	v_or_b32_e32 v12, s6, v17
	v_ashrrev_i32_e32 v13, 31, v12
	v_lshlrev_b64 v[8:9], 11, v[12:13]
	v_lshl_add_u64 v[10:11], v[6:7], 0, v[4:5]
	v_lshl_add_u64 v[14:15], v[6:7], 0, v[8:9]
	s_mov_b64 s[18:19], 0
	v_mov_b32_e32 v0, 0
	v_mov_b32_e32 v1, v5
	v_mov_b32_e32 v2, v5
	v_mov_b32_e32 v3, v5
	s_cmpk_lg_i32 s34, 0x100
	s_cbranch_scc1 .LBB0_1169
	s_waitcnt vmcnt(0)
	s_and_b32 s20, s3, 63
	v_lshl_or_b32 v24, s20, 4, v18
	v_lshlrev_b64 v[14:15], 12, v[12:13]
	v_lshl_add_u64 v[10:11], s[10:11], 0, v[14:15]
	v_lshlrev_b32_e32 v4, 2, v24
	v_lshl_add_u64 v[10:11], v[10:11], 0, v[4:5]
	v_add_co_u32_e32 v10, vcc, 0xf8000000, v10
	v_lshl_add_u64 v[14:15], s[90:91], 0, v[14:15]
	s_nop 0
	v_addc_co_u32_e32 v11, vcc, -1, v11, vcc
	global_load_dwordx4 v[10:13], v[10:11], off
	s_lshr_b32 s100, s2, 3
	s_lshl_b32 s100, s100, 4
	s_add_i32 s100, s100, 0x8000
	s_mul_i32 s100, s100, 0x800
	s_add_u32 s96, s92, s100
	s_addc_u32 s97, s93, 0
	s_add_u32 s96, s96, 0x15780000
	s_addc_u32 s97, s97, 0
	s_and_b32 s100, s2, 7
	s_lshl_b32 s100, s100, 7
	s_mul_i32 s100, s100, 0x800
	s_add_u32 s98, s92, s100
	s_addc_u32 s99, s93, 0
	s_add_u32 s98, s98, 0x1040000
	s_addc_u32 s99, s99, 0
	v_lshrrev_b32_e32 v179, 4, v200
	v_and_b32_e32 v180, 15, v200
	v_and_b32_e32 v181, 15, v179
	v_xor_b32_e32 v180, v180, v181
	v_lshlrev_b32_e32 v180, 4, v180
	s_mov_b32 s100, 0x800
	v_mad_u32_u24 v164, v179, s100, v180
	v_add_u32_e32 v165, 0x10000, v164
	v_add_u32_e32 v166, 0x20000, v164
	v_add_u32_e32 v167, 0x30000, v164
	v_mad_u32_u24 v168, v181, s100, v180
	v_lshlrev_b32_e32 v169, 4, v200
	v_add_u32_e32 v169, 1024, v169
	v_and_b32_e32 v170, 0xff, v200
	v_lshlrev_b32_e32 v170, 4, v170
	v_add_u32_e32 v170, 33792, v170
	v_and_b32_e32 v179, 15, v200
	v_bfe_u32 v180, v200, 4, 2
	v_and_b32_e32 v181, 3, v179
	v_xor_b32_e32 v180, v180, v181
	v_lshlrev_b32_e32 v180, 4, v180
	v_lshrrev_b32_e32 v181, 2, v179
	v_lshl_add_u32 v180, v181, 6, v180
	v_lshl_add_u32 v180, v179, 8, v180
	v_add_u32_e32 v171, 33792, v180
	v_lshrrev_b32_e32 v181, 6, v200
	v_lshlrev_b32_e32 v181, 12, v181
	v_add_u32_e32 v175, v180, v181
	v_add_u32_e32 v175, 1024, v175
	v_xor_b32_e32 v172, 0x40, v171
	v_xor_b32_e32 v176, 0x40, v175
	v_xor_b32_e32 v173, 0x80, v171
	v_xor_b32_e32 v177, 0x80, v175
	v_xor_b32_e32 v174, 0xc0, v171
	v_xor_b32_e32 v178, 0xc0, v175
	global_load_dwordx4 v[64:67], v164, s[98:99]
	global_load_dwordx4 v[68:71], v165, s[98:99]
	global_load_dwordx4 v[72:75], v166, s[98:99]
	global_load_dwordx4 v[76:79], v167, s[98:99]
	global_load_dwordx4 v[80:83], v168, s[96:97]
	s_add_u32 s98, s98, 0x100
	s_addc_u32 s99, s99, 0
	s_add_u32 s96, s96, 0x100
	s_addc_u32 s97, s97, 0
	global_load_dwordx4 v[84:87], v164, s[98:99]
	global_load_dwordx4 v[88:91], v165, s[98:99]
	global_load_dwordx4 v[92:95], v166, s[98:99]
	global_load_dwordx4 v[96:99], v167, s[98:99]
	global_load_dwordx4 v[100:103], v168, s[96:97]
	s_add_u32 s98, s98, 0x100
	s_addc_u32 s99, s99, 0
	s_add_u32 s96, s96, 0x100
	s_addc_u32 s97, s97, 0
	global_load_dwordx4 v[104:107], v164, s[98:99]
	global_load_dwordx4 v[108:111], v165, s[98:99]
	global_load_dwordx4 v[112:115], v166, s[98:99]
	global_load_dwordx4 v[116:119], v167, s[98:99]
	global_load_dwordx4 v[120:123], v168, s[96:97]
	s_add_u32 s98, s98, 0x100
	s_addc_u32 s99, s99, 0
	s_add_u32 s96, s96, 0x100
	s_addc_u32 s97, s97, 0
	global_load_dwordx4 v[124:127], v164, s[98:99]
	global_load_dwordx4 v[128:131], v165, s[98:99]
	global_load_dwordx4 v[132:135], v166, s[98:99]
	global_load_dwordx4 v[136:139], v167, s[98:99]
	global_load_dwordx4 v[140:143], v168, s[96:97]
	s_add_u32 s98, s98, 0x100
	s_addc_u32 s99, s99, 0
	s_add_u32 s96, s96, 0x100
	s_addc_u32 s97, s97, 0
	global_load_dwordx4 v[144:147], v164, s[98:99]
	global_load_dwordx4 v[148:151], v165, s[98:99]
	global_load_dwordx4 v[152:155], v166, s[98:99]
	global_load_dwordx4 v[156:159], v167, s[98:99]
	global_load_dwordx4 v[160:163], v168, s[96:97]
	s_add_u32 s98, s98, 0x100
	s_addc_u32 s99, s99, 0
	s_add_u32 s96, s96, 0x100
	s_addc_u32 s97, s97, 0
	s_waitcnt vmcnt(24)
	ds_write_b128 v169, v[64:67]
	s_waitcnt vmcnt(23)
	ds_write_b128 v169, v[68:71] offset:8192
	s_waitcnt vmcnt(22)
	ds_write_b128 v169, v[72:75] offset:16384
	s_waitcnt vmcnt(21)
	ds_write_b128 v169, v[76:79] offset:24576
	s_waitcnt vmcnt(20)
	ds_write_b128 v170, v[80:83]
	s_waitcnt lgkmcnt(0)
	s_barrier
	s_waitcnt vmcnt(19)
	ds_write_b128 v169, v[84:87] offset:36864
	s_waitcnt vmcnt(18)
	ds_write_b128 v169, v[88:91] offset:45056
	s_waitcnt vmcnt(17)
	ds_write_b128 v169, v[92:95] offset:53248
	s_waitcnt vmcnt(16)
	ds_write_b128 v169, v[96:99] offset:61440
	s_waitcnt vmcnt(15)
	ds_write_b128 v170, v[100:103] offset:36864
	global_load_dwordx4 v[64:67], v164, s[98:99]
	global_load_dwordx4 v[68:71], v165, s[98:99]
	global_load_dwordx4 v[72:75], v166, s[98:99]
	global_load_dwordx4 v[76:79], v167, s[98:99]
	global_load_dwordx4 v[80:83], v168, s[96:97]
	s_add_u32 s98, s98, 0x100
	s_addc_u32 s99, s99, 0
	s_add_u32 s96, s96, 0x100
	s_addc_u32 s97, s97, 0
	ds_read_b128 v[204:207], v175
	ds_read_b128 v[208:211], v171
	ds_read_b128 v[212:215], v176
	ds_read_b128 v[216:219], v172
	ds_read_b128 v[220:223], v177
	ds_read_b128 v[224:227], v173
	ds_read_b128 v[228:231], v178
	ds_read_b128 v[232:235], v174
	s_waitcnt lgkmcnt(6)
	v_mfma_f32_16x16x32_bf16 v[0:3], v[204:207], v[208:211], v[0:3]
	s_waitcnt lgkmcnt(4)
	v_mfma_f32_16x16x32_bf16 v[0:3], v[212:215], v[216:219], v[0:3]
	s_waitcnt lgkmcnt(2)
	v_mfma_f32_16x16x32_bf16 v[0:3], v[220:223], v[224:227], v[0:3]
	s_waitcnt lgkmcnt(0)
	v_mfma_f32_16x16x32_bf16 v[0:3], v[228:231], v[232:235], v[0:3]
	s_waitcnt lgkmcnt(0)
	s_barrier
; template <int MODE>
; __device__ __forceinline__ void sgemm_sample(LAS unsigned char* lds, const bf16_t* A, const bf16_t* Bt, int K, const float* resid, float* out, bf16_t* xb, float* ssq_out, const float* ssq_in) {
;     ...
; #pragma unroll 8
;         for (int ks = 0; ks < K / 32; ++ks) {
;             const bf16x8 a = *(const bf16x8*)(ap + ks * 32); const bf16x8 b = *(const bf16x8*)(bp + ks * 32);
;             acc = __builtin_amdgcn_mfma_f32_16x16x32_bf16(b, a, acc, 0, 0, 0);
;         }
	s_waitcnt vmcnt(19)
	ds_write_b128 v169, v[104:107]
	s_waitcnt vmcnt(18)
	ds_write_b128 v169, v[108:111] offset:8192
	s_waitcnt vmcnt(17)
	ds_write_b128 v169, v[112:115] offset:16384
	s_waitcnt vmcnt(16)
	ds_write_b128 v169, v[116:119] offset:24576
	s_waitcnt vmcnt(15)
	ds_write_b128 v170, v[120:123]
	global_load_dwordx4 v[84:87], v164, s[98:99]
	global_load_dwordx4 v[88:91], v165, s[98:99]
	global_load_dwordx4 v[92:95], v166, s[98:99]
	global_load_dwordx4 v[96:99], v167, s[98:99]
	global_load_dwordx4 v[100:103], v168, s[96:97]
	s_add_u32 s98, s98, 0x100
	s_addc_u32 s99, s99, 0
	s_add_u32 s96, s96, 0x100
	s_addc_u32 s97, s97, 0
	ds_read_b128 v[204:207], v175 offset:36864
	ds_read_b128 v[208:211], v171 offset:36864
	ds_read_b128 v[212:215], v176 offset:36864
	ds_read_b128 v[216:219], v172 offset:36864
	ds_read_b128 v[220:223], v177 offset:36864
	ds_read_b128 v[224:227], v173 offset:36864
	ds_read_b128 v[228:231], v178 offset:36864
	ds_read_b128 v[232:235], v174 offset:36864
	s_waitcnt lgkmcnt(6)
	v_mfma_f32_16x16x32_bf16 v[0:3], v[204:207], v[208:211], v[0:3]
	s_waitcnt lgkmcnt(4)
	v_mfma_f32_16x16x32_bf16 v[0:3], v[212:215], v[216:219], v[0:3]
	s_waitcnt lgkmcnt(2)
	v_mfma_f32_16x16x32_bf16 v[0:3], v[220:223], v[224:227], v[0:3]
	s_waitcnt lgkmcnt(0)
	v_mfma_f32_16x16x32_bf16 v[0:3], v[228:231], v[232:235], v[0:3]
	s_waitcnt lgkmcnt(0)
	s_barrier
	s_waitcnt vmcnt(19)
	ds_write_b128 v169, v[124:127] offset:36864
	s_waitcnt vmcnt(18)
	ds_write_b128 v169, v[128:131] offset:45056
	s_waitcnt vmcnt(17)
	ds_write_b128 v169, v[132:135] offset:53248
	s_waitcnt vmcnt(16)
	ds_write_b128 v169, v[136:139] offset:61440
	s_waitcnt vmcnt(15)
	ds_write_b128 v170, v[140:143] offset:36864
	global_load_dwordx4 v[104:107], v164, s[98:99]
	global_load_dwordx4 v[108:111], v165, s[98:99]
	global_load_dwordx4 v[112:115], v166, s[98:99]
	global_load_dwordx4 v[116:119], v167, s[98:99]
	global_load_dwordx4 v[120:123], v168, s[96:97]
	s_add_u32 s98, s98, 0x100
	s_addc_u32 s99, s99, 0
	s_add_u32 s96, s96, 0x100
	s_addc_u32 s97, s97, 0
	ds_read_b128 v[204:207], v175
	ds_read_b128 v[208:211], v171
	ds_read_b128 v[212:215], v176
	ds_read_b128 v[216:219], v172
	ds_read_b128 v[220:223], v177
	ds_read_b128 v[224:227], v173
	ds_read_b128 v[228:231], v178
	ds_read_b128 v[232:235], v174
	s_waitcnt lgkmcnt(6)
	v_mfma_f32_16x16x32_bf16 v[0:3], v[204:207], v[208:211], v[0:3]
	s_waitcnt lgkmcnt(4)
	v_mfma_f32_16x16x32_bf16 v[0:3], v[212:215], v[216:219], v[0:3]
	s_waitcnt lgkmcnt(2)
	v_mfma_f32_16x16x32_bf16 v[0:3], v[220:223], v[224:227], v[0:3]
	s_waitcnt lgkmcnt(0)
	v_mfma_f32_16x16x32_bf16 v[0:3], v[228:231], v[232:235], v[0:3]
	s_waitcnt lgkmcnt(0)
	s_barrier
	s_waitcnt vmcnt(19)
	ds_write_b128 v169, v[144:147]
	s_waitcnt vmcnt(18)
	ds_write_b128 v169, v[148:151] offset:8192
	s_waitcnt vmcnt(17)
	ds_write_b128 v169, v[152:155] offset:16384
	s_waitcnt vmcnt(16)
	ds_write_b128 v169, v[156:159] offset:24576
	s_waitcnt vmcnt(15)
	ds_write_b128 v170, v[160:163]
	ds_read_b128 v[204:207], v175 offset:36864
	ds_read_b128 v[208:211], v171 offset:36864
	ds_read_b128 v[212:215], v176 offset:36864
	ds_read_b128 v[216:219], v172 offset:36864
	ds_read_b128 v[220:223], v177 offset:36864
	ds_read_b128 v[224:227], v173 offset:36864
	ds_read_b128 v[228:231], v178 offset:36864
	ds_read_b128 v[232:235], v174 offset:36864
	s_waitcnt lgkmcnt(6)
	v_mfma_f32_16x16x32_bf16 v[0:3], v[204:207], v[208:211], v[0:3]
	s_waitcnt lgkmcnt(4)
	v_mfma_f32_16x16x32_bf16 v[0:3], v[212:215], v[216:219], v[0:3]
	s_waitcnt lgkmcnt(2)
	v_mfma_f32_16x16x32_bf16 v[0:3], v[220:223], v[224:227], v[0:3]
	s_waitcnt lgkmcnt(0)
	v_mfma_f32_16x16x32_bf16 v[0:3], v[228:231], v[232:235], v[0:3]
	s_waitcnt lgkmcnt(0)
	s_barrier
; template <int MODE>
; __device__ __forceinline__ void sgemm_sample(LAS unsigned char* lds, const bf16_t* A, const bf16_t* Bt, int K, const float* resid, float* out, bf16_t* xb, float* ssq_out, const float* ssq_in) {
;     ...
; #pragma unroll 8
;         for (int ks = 0; ks < K / 32; ++ks) {
;             const bf16x8 a = *(const bf16x8*)(ap + ks * 32); const bf16x8 b = *(const bf16x8*)(bp + ks * 32);
;             acc = __builtin_amdgcn_mfma_f32_16x16x32_bf16(b, a, acc, 0, 0, 0);
;         }
	s_waitcnt vmcnt(14)
	ds_write_b128 v169, v[64:67] offset:36864
	s_waitcnt vmcnt(13)
	ds_write_b128 v169, v[68:71] offset:45056
	s_waitcnt vmcnt(12)
	ds_write_b128 v169, v[72:75] offset:53248
	s_waitcnt vmcnt(11)
	ds_write_b128 v169, v[76:79] offset:61440
	s_waitcnt vmcnt(10)
	ds_write_b128 v170, v[80:83] offset:36864
	ds_read_b128 v[204:207], v175
	ds_read_b128 v[208:211], v171
	ds_read_b128 v[212:215], v176
	ds_read_b128 v[216:219], v172
	ds_read_b128 v[220:223], v177
	ds_read_b128 v[224:227], v173
	ds_read_b128 v[228:231], v178
	ds_read_b128 v[232:235], v174
	s_waitcnt lgkmcnt(6)
	v_mfma_f32_16x16x32_bf16 v[0:3], v[204:207], v[208:211], v[0:3]
	s_waitcnt lgkmcnt(4)
	v_mfma_f32_16x16x32_bf16 v[0:3], v[212:215], v[216:219], v[0:3]
	s_waitcnt lgkmcnt(2)
	v_mfma_f32_16x16x32_bf16 v[0:3], v[220:223], v[224:227], v[0:3]
	s_waitcnt lgkmcnt(0)
	v_mfma_f32_16x16x32_bf16 v[0:3], v[228:231], v[232:235], v[0:3]
	s_waitcnt lgkmcnt(0)
	s_barrier
	s_waitcnt vmcnt(9)
	ds_write_b128 v169, v[84:87]
	s_waitcnt vmcnt(8)
	ds_write_b128 v169, v[88:91] offset:8192
	s_waitcnt vmcnt(7)
	ds_write_b128 v169, v[92:95] offset:16384
	s_waitcnt vmcnt(6)
	ds_write_b128 v169, v[96:99] offset:24576
	s_waitcnt vmcnt(5)
	ds_write_b128 v170, v[100:103]
	ds_read_b128 v[204:207], v175 offset:36864
	ds_read_b128 v[208:211], v171 offset:36864
	ds_read_b128 v[212:215], v176 offset:36864
	ds_read_b128 v[216:219], v172 offset:36864
	ds_read_b128 v[220:223], v177 offset:36864
	ds_read_b128 v[224:227], v173 offset:36864
	ds_read_b128 v[228:231], v178 offset:36864
	ds_read_b128 v[232:235], v174 offset:36864
	s_waitcnt lgkmcnt(6)
	v_mfma_f32_16x16x32_bf16 v[0:3], v[204:207], v[208:211], v[0:3]
	s_waitcnt lgkmcnt(4)
	v_mfma_f32_16x16x32_bf16 v[0:3], v[212:215], v[216:219], v[0:3]
	s_waitcnt lgkmcnt(2)
	v_mfma_f32_16x16x32_bf16 v[0:3], v[220:223], v[224:227], v[0:3]
	s_waitcnt lgkmcnt(0)
	v_mfma_f32_16x16x32_bf16 v[0:3], v[228:231], v[232:235], v[0:3]
	s_waitcnt lgkmcnt(0)
	s_barrier
	s_waitcnt vmcnt(4)
	ds_write_b128 v169, v[104:107] offset:36864
	s_waitcnt vmcnt(3)
	ds_write_b128 v169, v[108:111] offset:45056
	s_waitcnt vmcnt(2)
	ds_write_b128 v169, v[112:115] offset:53248
	s_waitcnt vmcnt(1)
	ds_write_b128 v169, v[116:119] offset:61440
	s_waitcnt vmcnt(0)
	ds_write_b128 v170, v[120:123] offset:36864
	ds_read_b128 v[204:207], v175
	ds_read_b128 v[208:211], v171
	ds_read_b128 v[212:215], v176
	ds_read_b128 v[216:219], v172
	ds_read_b128 v[220:223], v177
	ds_read_b128 v[224:227], v173
	ds_read_b128 v[228:231], v178
	ds_read_b128 v[232:235], v174
	s_waitcnt lgkmcnt(6)
	v_mfma_f32_16x16x32_bf16 v[0:3], v[204:207], v[208:211], v[0:3]
	s_waitcnt lgkmcnt(4)
	v_mfma_f32_16x16x32_bf16 v[0:3], v[212:215], v[216:219], v[0:3]
	s_waitcnt lgkmcnt(2)
	v_mfma_f32_16x16x32_bf16 v[0:3], v[220:223], v[224:227], v[0:3]
	s_waitcnt lgkmcnt(0)
	v_mfma_f32_16x16x32_bf16 v[0:3], v[228:231], v[232:235], v[0:3]
	s_waitcnt lgkmcnt(0)
	s_barrier
	ds_read_b128 v[204:207], v175 offset:36864
	ds_read_b128 v[208:211], v171 offset:36864
	ds_read_b128 v[212:215], v176 offset:36864
	ds_read_b128 v[216:219], v172 offset:36864
	ds_read_b128 v[220:223], v177 offset:36864
	ds_read_b128 v[224:227], v173 offset:36864
	ds_read_b128 v[228:231], v178 offset:36864
	ds_read_b128 v[232:235], v174 offset:36864
	s_waitcnt lgkmcnt(6)
	v_mfma_f32_16x16x32_bf16 v[0:3], v[204:207], v[208:211], v[0:3]
	s_waitcnt lgkmcnt(4)
	v_mfma_f32_16x16x32_bf16 v[0:3], v[212:215], v[216:219], v[0:3]
	s_waitcnt lgkmcnt(2)
	v_mfma_f32_16x16x32_bf16 v[0:3], v[220:223], v[224:227], v[0:3]
	s_waitcnt lgkmcnt(0)
	v_mfma_f32_16x16x32_bf16 v[0:3], v[228:231], v[232:235], v[0:3]
	s_nop 7
	s_nop 7
	s_nop 3
	s_branch .Lsgx2_done

; template <int MODE>
; __device__ __forceinline__ void sgemm_sample(LAS unsigned char* lds, const bf16_t* A, const bf16_t* Bt, int K, const float* resid, float* out, bf16_t* xb, float* ssq_out, const float* ssq_in) {
;     ...
;     for (int uu = u; uu < 2048; uu += gridDim.x * 8) {
;         const int rt = uu >> 6, ct = uu & 63; const int row = NTOKP + rt * 16 + fr, col0 = ct * 16 + fq * 4;
;         const bf16_t* ap = A + (size_t)row * K + fq * 8; const bf16_t* bp = Bt + (size_t)(ct * 16 + fr) * K + fq * 8;
;         f32x4 acc = {0.f, 0.f, 0.f, 0.f};
; #pragma unroll 8
;         for (int ks = 0; ks < K / 32; ++ks) {
;             const bf16x8 a = *(const bf16x8*)(ap + ks * 32); const bf16x8 b = *(const bf16x8*)(bp + ks * 32);
;             acc = __builtin_amdgcn_mfma_f32_16x16x32_bf16(b, a, acc, 0, 0, 0);
;         }
;         if (MODE == 0) {
;             const f32x4 x = *(const f32x4*)(resid + (size_t)(row - NTOKP) * D + col0) + acc;
.LBB0_1348:
	s_ashr_i32 s0, s3, 2
	s_and_b32 s0, s0, -16
	v_add_u32_e32 v8, s0, v16
	s_lshl_b32 s0, s3, 4
	s_and_b32 s10, s0, 0x3f0
	v_or_b32_e32 v0, s10, v14
	v_mul_u32_u24_e32 v0, 0xb00, v0
	v_mad_i64_i32 v[10:11], s[0:1], v8, s5, v[6:7]
	v_lshlrev_b32_e32 v4, 1, v0
	v_ashrrev_i32_e32 v9, 31, v8
	v_lshl_add_u64 v[12:13], v[6:7], 0, v[4:5]
	s_mov_b64 s[0:1], 0
	v_mov_b32_e32 v0, 0
	s_waitcnt lgkmcnt(0)
	v_mov_b32_e32 v1, v5
	v_mov_b32_e32 v2, v5
	v_mov_b32_e32 v3, v5
	s_cmpk_lg_i32 s34, 0x100
	s_cbranch_scc1 .LBB0_1349
	s_waitcnt vmcnt(0)
	v_or_b32_e32 v4, s10, v15
	v_lshlrev_b64 v[12:13], 12, v[8:9]
	v_lshl_add_u64 v[8:9], s[8:9], 0, v[12:13]
	v_lshlrev_b32_e32 v4, 2, v4
	v_lshl_add_u64 v[8:9], v[8:9], 0, v[4:5]
	v_add_co_u32_e32 v8, vcc, 0xf8000000, v8
	s_add_i32 s3, s3, s4
	s_nop 0
	v_addc_co_u32_e32 v9, vcc, -1, v9, vcc
	global_load_dwordx4 v[8:11], v[8:9], off
	s_lshr_b32 s100, s2, 3
	s_lshl_b32 s100, s100, 4
	s_add_i32 s100, s100, 0x8000
	s_mul_i32 s100, s100, 0x1600
	s_add_u32 s96, s92, s100
	s_addc_u32 s97, s93, 0
	s_add_u32 s96, s96, 0x22c0000
	s_addc_u32 s97, s97, 0
	s_and_b32 s100, s2, 7
	s_lshl_b32 s100, s100, 7
	s_mul_i32 s100, s100, 0x1600
	s_add_u32 s98, s92, s100
	s_addc_u32 s99, s93, 0
	s_add_u32 s98, s98, 0x1d40000
	s_addc_u32 s99, s99, 0
	v_lshrrev_b32_e32 v179, 4, v200
	v_and_b32_e32 v180, 15, v200
	v_and_b32_e32 v181, 15, v179
	v_xor_b32_e32 v180, v180, v181
	v_lshlrev_b32_e32 v180, 4, v180
	s_mov_b32 s100, 0x1600
	v_mad_u32_u24 v164, v179, s100, v180
	v_add_u32_e32 v165, 0x2c000, v164
	v_add_u32_e32 v166, 0x58000, v164
	v_add_u32_e32 v167, 0x84000, v164
	v_mad_u32_u24 v168, v181, s100, v180
	v_lshlrev_b32_e32 v169, 4, v200
	v_add_u32_e32 v169, 1024, v169
	v_and_b32_e32 v170, 0xff, v200
	v_lshlrev_b32_e32 v170, 4, v170
	v_add_u32_e32 v170, 33792, v170
	v_and_b32_e32 v179, 15, v200
	v_bfe_u32 v180, v200, 4, 2
	v_and_b32_e32 v181, 3, v179
	v_xor_b32_e32 v180, v180, v181
	v_lshlrev_b32_e32 v180, 4, v180
	v_lshrrev_b32_e32 v181, 2, v179
	v_lshl_add_u32 v180, v181, 6, v180
	v_lshl_add_u32 v180, v179, 8, v180
	v_add_u32_e32 v171, 33792, v180
	v_lshrrev_b32_e32 v181, 6, v200
	v_lshlrev_b32_e32 v181, 12, v181
	v_add_u32_e32 v175, v180, v181
	v_add_u32_e32 v175, 1024, v175
	v_xor_b32_e32 v172, 0x40, v171
	v_xor_b32_e32 v176, 0x40, v175
	v_xor_b32_e32 v173, 0x80, v171
	v_xor_b32_e32 v177, 0x80, v175
	v_xor_b32_e32 v174, 0xc0, v171
	v_xor_b32_e32 v178, 0xc0, v175
	global_load_dwordx4 v[64:67], v164, s[98:99]
	global_load_dwordx4 v[68:71], v165, s[98:99]
	global_load_dwordx4 v[72:75], v166, s[98:99]
	global_load_dwordx4 v[76:79], v167, s[98:99]
	global_load_dwordx4 v[80:83], v168, s[96:97]
	s_add_u32 s98, s98, 0x100
	s_addc_u32 s99, s99, 0
	s_add_u32 s96, s96, 0x100
	s_addc_u32 s97, s97, 0
	global_load_dwordx4 v[84:87], v164, s[98:99]
	global_load_dwordx4 v[88:91], v165, s[98:99]
	global_load_dwordx4 v[92:95], v166, s[98:99]
	global_load_dwordx4 v[96:99], v167, s[98:99]
	global_load_dwordx4 v[100:103], v168, s[96:97]
	s_add_u32 s98, s98, 0x100
	s_addc_u32 s99, s99, 0
	s_add_u32 s96, s96, 0x100
	s_addc_u32 s97, s97, 0
	global_load_dwordx4 v[104:107], v164, s[98:99]
	global_load_dwordx4 v[108:111], v165, s[98:99]
	global_load_dwordx4 v[112:115], v166, s[98:99]
	global_load_dwordx4 v[116:119], v167, s[98:99]
	global_load_dwordx4 v[120:123], v168, s[96:97]
	s_add_u32 s98, s98, 0x100
	s_addc_u32 s99, s99, 0
	s_add_u32 s96, s96, 0x100
	s_addc_u32 s97, s97, 0
	global_load_dwordx4 v[124:127], v164, s[98:99]
	global_load_dwordx4 v[128:131], v165, s[98:99]
	global_load_dwordx4 v[132:135], v166, s[98:99]
	global_load_dwordx4 v[136:139], v167, s[98:99]
	global_load_dwordx4 v[140:143], v168, s[96:97]
	s_add_u32 s98, s98, 0x100
	s_addc_u32 s99, s99, 0
	s_add_u32 s96, s96, 0x100
	s_addc_u32 s97, s97, 0
	global_load_dwordx4 v[144:147], v164, s[98:99]
	global_load_dwordx4 v[148:151], v165, s[98:99]
	global_load_dwordx4 v[152:155], v166, s[98:99]
	global_load_dwordx4 v[156:159], v167, s[98:99]
	global_load_dwordx4 v[160:163], v168, s[96:97]
	s_add_u32 s98, s98, 0x100
	s_addc_u32 s99, s99, 0
	s_add_u32 s96, s96, 0x100
	s_addc_u32 s97, s97, 0
	s_waitcnt vmcnt(24)
	ds_write_b128 v169, v[64:67]
	s_waitcnt vmcnt(23)
	ds_write_b128 v169, v[68:71] offset:8192
	s_waitcnt vmcnt(22)
	ds_write_b128 v169, v[72:75] offset:16384
	s_waitcnt vmcnt(21)
	ds_write_b128 v169, v[76:79] offset:24576
	s_waitcnt vmcnt(20)
	ds_write_b128 v170, v[80:83]
	s_waitcnt lgkmcnt(0)
	s_barrier
	s_waitcnt vmcnt(19)
	ds_write_b128 v169, v[84:87] offset:36864
	s_waitcnt vmcnt(18)
	ds_write_b128 v169, v[88:91] offset:45056
	s_waitcnt vmcnt(17)
	ds_write_b128 v169, v[92:95] offset:53248
	s_waitcnt vmcnt(16)
	ds_write_b128 v169, v[96:99] offset:61440
	s_waitcnt vmcnt(15)
	ds_write_b128 v170, v[100:103] offset:36864
	global_load_dwordx4 v[64:67], v164, s[98:99]
	global_load_dwordx4 v[68:71], v165, s[98:99]
	global_load_dwordx4 v[72:75], v166, s[98:99]
	global_load_dwordx4 v[76:79], v167, s[98:99]
	global_load_dwordx4 v[80:83], v168, s[96:97]
	s_add_u32 s98, s98, 0x100
	s_addc_u32 s99, s99, 0
	s_add_u32 s96, s96, 0x100
	s_addc_u32 s97, s97, 0
	ds_read_b128 v[204:207], v175
	ds_read_b128 v[208:211], v171
	ds_read_b128 v[212:215], v176
	ds_read_b128 v[216:219], v172
	ds_read_b128 v[220:223], v177
	ds_read_b128 v[224:227], v173
	ds_read_b128 v[228:231], v178
	ds_read_b128 v[232:235], v174
	s_waitcnt lgkmcnt(6)
	v_mfma_f32_16x16x32_bf16 v[0:3], v[204:207], v[208:211], v[0:3]
	s_waitcnt lgkmcnt(4)
	v_mfma_f32_16x16x32_bf16 v[0:3], v[212:215], v[216:219], v[0:3]
	s_waitcnt lgkmcnt(2)
	v_mfma_f32_16x16x32_bf16 v[0:3], v[220:223], v[224:227], v[0:3]
	s_waitcnt lgkmcnt(0)
	v_mfma_f32_16x16x32_bf16 v[0:3], v[228:231], v[232:235], v[0:3]
	s_waitcnt lgkmcnt(0)
	s_barrier
; template <int MODE>
; __device__ __forceinline__ void sgemm_sample(LAS unsigned char* lds, const bf16_t* A, const bf16_t* Bt, int K, const float* resid, float* out, bf16_t* xb, float* ssq_out, const float* ssq_in) {
;     ...
; #pragma unroll 8
;         for (int ks = 0; ks < K / 32; ++ks) {
;             const bf16x8 a = *(const bf16x8*)(ap + ks * 32); const bf16x8 b = *(const bf16x8*)(bp + ks * 32);
;             acc = __builtin_amdgcn_mfma_f32_16x16x32_bf16(b, a, acc, 0, 0, 0);
;         }
	s_waitcnt vmcnt(19)
	ds_write_b128 v169, v[104:107]
	s_waitcnt vmcnt(18)
	ds_write_b128 v169, v[108:111] offset:8192
	s_waitcnt vmcnt(17)
	ds_write_b128 v169, v[112:115] offset:16384
	s_waitcnt vmcnt(16)
	ds_write_b128 v169, v[116:119] offset:24576
	s_waitcnt vmcnt(15)
	ds_write_b128 v170, v[120:123]
	global_load_dwordx4 v[84:87], v164, s[98:99]
	global_load_dwordx4 v[88:91], v165, s[98:99]
	global_load_dwordx4 v[92:95], v166, s[98:99]
	global_load_dwordx4 v[96:99], v167, s[98:99]
	global_load_dwordx4 v[100:103], v168, s[96:97]
	s_add_u32 s98, s98, 0x100
	s_addc_u32 s99, s99, 0
	s_add_u32 s96, s96, 0x100
	s_addc_u32 s97, s97, 0
	ds_read_b128 v[204:207], v175 offset:36864
	ds_read_b128 v[208:211], v171 offset:36864
	ds_read_b128 v[212:215], v176 offset:36864
	ds_read_b128 v[216:219], v172 offset:36864
	ds_read_b128 v[220:223], v177 offset:36864
	ds_read_b128 v[224:227], v173 offset:36864
	ds_read_b128 v[228:231], v178 offset:36864
	ds_read_b128 v[232:235], v174 offset:36864
	s_waitcnt lgkmcnt(6)
	v_mfma_f32_16x16x32_bf16 v[0:3], v[204:207], v[208:211], v[0:3]
	s_waitcnt lgkmcnt(4)
	v_mfma_f32_16x16x32_bf16 v[0:3], v[212:215], v[216:219], v[0:3]
	s_waitcnt lgkmcnt(2)
	v_mfma_f32_16x16x32_bf16 v[0:3], v[220:223], v[224:227], v[0:3]
	s_waitcnt lgkmcnt(0)
	v_mfma_f32_16x16x32_bf16 v[0:3], v[228:231], v[232:235], v[0:3]
	s_waitcnt lgkmcnt(0)
	s_barrier
	s_waitcnt vmcnt(19)
	ds_write_b128 v169, v[124:127] offset:36864
	s_waitcnt vmcnt(18)
	ds_write_b128 v169, v[128:131] offset:45056
	s_waitcnt vmcnt(17)
	ds_write_b128 v169, v[132:135] offset:53248
	s_waitcnt vmcnt(16)
	ds_write_b128 v169, v[136:139] offset:61440
	s_waitcnt vmcnt(15)
	ds_write_b128 v170, v[140:143] offset:36864
	global_load_dwordx4 v[104:107], v164, s[98:99]
	global_load_dwordx4 v[108:111], v165, s[98:99]
	global_load_dwordx4 v[112:115], v166, s[98:99]
	global_load_dwordx4 v[116:119], v167, s[98:99]
	global_load_dwordx4 v[120:123], v168, s[96:97]
	s_add_u32 s98, s98, 0x100
	s_addc_u32 s99, s99, 0
	s_add_u32 s96, s96, 0x100
	s_addc_u32 s97, s97, 0
	ds_read_b128 v[204:207], v175
	ds_read_b128 v[208:211], v171
	ds_read_b128 v[212:215], v176
	ds_read_b128 v[216:219], v172
	ds_read_b128 v[220:223], v177
	ds_read_b128 v[224:227], v173
	ds_read_b128 v[228:231], v178
	ds_read_b128 v[232:235], v174
	s_waitcnt lgkmcnt(6)
	v_mfma_f32_16x16x32_bf16 v[0:3], v[204:207], v[208:211], v[0:3]
	s_waitcnt lgkmcnt(4)
	v_mfma_f32_16x16x32_bf16 v[0:3], v[212:215], v[216:219], v[0:3]
	s_waitcnt lgkmcnt(2)
	v_mfma_f32_16x16x32_bf16 v[0:3], v[220:223], v[224:227], v[0:3]
	s_waitcnt lgkmcnt(0)
	v_mfma_f32_16x16x32_bf16 v[0:3], v[228:231], v[232:235], v[0:3]
	s_waitcnt lgkmcnt(0)
	s_barrier
	s_waitcnt vmcnt(19)
	ds_write_b128 v169, v[144:147]
	s_waitcnt vmcnt(18)
	ds_write_b128 v169, v[148:151] offset:8192
	s_waitcnt vmcnt(17)
	ds_write_b128 v169, v[152:155] offset:16384
	s_waitcnt vmcnt(16)
	ds_write_b128 v169, v[156:159] offset:24576
	s_waitcnt vmcnt(15)
	ds_write_b128 v170, v[160:163]
	global_load_dwordx4 v[124:127], v164, s[98:99]
	global_load_dwordx4 v[128:131], v165, s[98:99]
	global_load_dwordx4 v[132:135], v166, s[98:99]
	global_load_dwordx4 v[136:139], v167, s[98:99]
	global_load_dwordx4 v[140:143], v168, s[96:97]
	s_add_u32 s98, s98, 0x100
	s_addc_u32 s99, s99, 0
	s_add_u32 s96, s96, 0x100
	s_addc_u32 s97, s97, 0
	ds_read_b128 v[204:207], v175 offset:36864
	ds_read_b128 v[208:211], v171 offset:36864
	ds_read_b128 v[212:215], v176 offset:36864
	ds_read_b128 v[216:219], v172 offset:36864
	ds_read_b128 v[220:223], v177 offset:36864
	ds_read_b128 v[224:227], v173 offset:36864
	ds_read_b128 v[228:231], v178 offset:36864
	ds_read_b128 v[232:235], v174 offset:36864
	s_waitcnt lgkmcnt(6)
	v_mfma_f32_16x16x32_bf16 v[0:3], v[204:207], v[208:211], v[0:3]
	s_waitcnt lgkmcnt(4)
	v_mfma_f32_16x16x32_bf16 v[0:3], v[212:215], v[216:219], v[0:3]
	s_waitcnt lgkmcnt(2)
	v_mfma_f32_16x16x32_bf16 v[0:3], v[220:223], v[224:227], v[0:3]
	s_waitcnt lgkmcnt(0)
	v_mfma_f32_16x16x32_bf16 v[0:3], v[228:231], v[232:235], v[0:3]
	s_waitcnt lgkmcnt(0)
	s_barrier
	s_waitcnt vmcnt(19)
	ds_write_b128 v169, v[64:67] offset:36864
	s_waitcnt vmcnt(18)
	ds_write_b128 v169, v[68:71] offset:45056
	s_waitcnt vmcnt(17)
	ds_write_b128 v169, v[72:75] offset:53248
	s_waitcnt vmcnt(16)
	ds_write_b128 v169, v[76:79] offset:61440
	s_waitcnt vmcnt(15)
	ds_write_b128 v170, v[80:83] offset:36864
	global_load_dwordx4 v[144:147], v164, s[98:99]
	global_load_dwordx4 v[148:151], v165, s[98:99]
	global_load_dwordx4 v[152:155], v166, s[98:99]
	global_load_dwordx4 v[156:159], v167, s[98:99]
	global_load_dwordx4 v[160:163], v168, s[96:97]
	s_add_u32 s98, s98, 0x100
	s_addc_u32 s99, s99, 0
	s_add_u32 s96, s96, 0x100
	s_addc_u32 s97, s97, 0
	ds_read_b128 v[204:207], v175
	ds_read_b128 v[208:211], v171
	ds_read_b128 v[212:215], v176
	ds_read_b128 v[216:219], v172
	ds_read_b128 v[220:223], v177
	ds_read_b128 v[224:227], v173
	ds_read_b128 v[228:231], v178
	ds_read_b128 v[232:235], v174
	s_waitcnt lgkmcnt(6)
	v_mfma_f32_16x16x32_bf16 v[0:3], v[204:207], v[208:211], v[0:3]
	s_waitcnt lgkmcnt(4)
	v_mfma_f32_16x16x32_bf16 v[0:3], v[212:215], v[216:219], v[0:3]
	s_waitcnt lgkmcnt(2)
	v_mfma_f32_16x16x32_bf16 v[0:3], v[220:223], v[224:227], v[0:3]
	s_waitcnt lgkmcnt(0)
	v_mfma_f32_16x16x32_bf16 v[0:3], v[228:231], v[232:235], v[0:3]
	s_waitcnt lgkmcnt(0)
	s_barrier
; template <int MODE>
; __device__ __forceinline__ void sgemm_sample(LAS unsigned char* lds, const bf16_t* A, const bf16_t* Bt, int K, const float* resid, float* out, bf16_t* xb, float* ssq_out, const float* ssq_in) {
;     ...
; #pragma unroll 8
;         for (int ks = 0; ks < K / 32; ++ks) {
;             const bf16x8 a = *(const bf16x8*)(ap + ks * 32); const bf16x8 b = *(const bf16x8*)(bp + ks * 32);
;             acc = __builtin_amdgcn_mfma_f32_16x16x32_bf16(b, a, acc, 0, 0, 0);
;         }
	s_waitcnt vmcnt(19)
	ds_write_b128 v169, v[84:87]
	s_waitcnt vmcnt(18)
	ds_write_b128 v169, v[88:91] offset:8192
	s_waitcnt vmcnt(17)
	ds_write_b128 v169, v[92:95] offset:16384
	s_waitcnt vmcnt(16)
	ds_write_b128 v169, v[96:99] offset:24576
	s_waitcnt vmcnt(15)
	ds_write_b128 v170, v[100:103]
	global_load_dwordx4 v[64:67], v164, s[98:99]
	global_load_dwordx4 v[68:71], v165, s[98:99]
	global_load_dwordx4 v[72:75], v166, s[98:99]
	global_load_dwordx4 v[76:79], v167, s[98:99]
	global_load_dwordx4 v[80:83], v168, s[96:97]
	s_add_u32 s98, s98, 0x100
	s_addc_u32 s99, s99, 0
	s_add_u32 s96, s96, 0x100
	s_addc_u32 s97, s97, 0
	ds_read_b128 v[204:207], v175 offset:36864
	ds_read_b128 v[208:211], v171 offset:36864
	ds_read_b128 v[212:215], v176 offset:36864
	ds_read_b128 v[216:219], v172 offset:36864
	ds_read_b128 v[220:223], v177 offset:36864
	ds_read_b128 v[224:227], v173 offset:36864
	ds_read_b128 v[228:231], v178 offset:36864
	ds_read_b128 v[232:235], v174 offset:36864
	s_waitcnt lgkmcnt(6)
	v_mfma_f32_16x16x32_bf16 v[0:3], v[204:207], v[208:211], v[0:3]
	s_waitcnt lgkmcnt(4)
	v_mfma_f32_16x16x32_bf16 v[0:3], v[212:215], v[216:219], v[0:3]
	s_waitcnt lgkmcnt(2)
	v_mfma_f32_16x16x32_bf16 v[0:3], v[220:223], v[224:227], v[0:3]
	s_waitcnt lgkmcnt(0)
	v_mfma_f32_16x16x32_bf16 v[0:3], v[228:231], v[232:235], v[0:3]
	s_waitcnt lgkmcnt(0)
	s_barrier
	s_waitcnt vmcnt(19)
	ds_write_b128 v169, v[104:107] offset:36864
	s_waitcnt vmcnt(18)
	ds_write_b128 v169, v[108:111] offset:45056
	s_waitcnt vmcnt(17)
	ds_write_b128 v169, v[112:115] offset:53248
	s_waitcnt vmcnt(16)
	ds_write_b128 v169, v[116:119] offset:61440
	s_waitcnt vmcnt(15)
	ds_write_b128 v170, v[120:123] offset:36864
	global_load_dwordx4 v[84:87], v164, s[98:99]
	global_load_dwordx4 v[88:91], v165, s[98:99]
	global_load_dwordx4 v[92:95], v166, s[98:99]
	global_load_dwordx4 v[96:99], v167, s[98:99]
	global_load_dwordx4 v[100:103], v168, s[96:97]
	s_add_u32 s98, s98, 0x100
	s_addc_u32 s99, s99, 0
	s_add_u32 s96, s96, 0x100
	s_addc_u32 s97, s97, 0
	ds_read_b128 v[204:207], v175
	ds_read_b128 v[208:211], v171
	ds_read_b128 v[212:215], v176
	ds_read_b128 v[216:219], v172
	ds_read_b128 v[220:223], v177
	ds_read_b128 v[224:227], v173
	ds_read_b128 v[228:231], v178
	ds_read_b128 v[232:235], v174
	s_waitcnt lgkmcnt(6)
	v_mfma_f32_16x16x32_bf16 v[0:3], v[204:207], v[208:211], v[0:3]
	s_waitcnt lgkmcnt(4)
	v_mfma_f32_16x16x32_bf16 v[0:3], v[212:215], v[216:219], v[0:3]
	s_waitcnt lgkmcnt(2)
	v_mfma_f32_16x16x32_bf16 v[0:3], v[220:223], v[224:227], v[0:3]
	s_waitcnt lgkmcnt(0)
	v_mfma_f32_16x16x32_bf16 v[0:3], v[228:231], v[232:235], v[0:3]
	s_waitcnt lgkmcnt(0)
	s_barrier
	s_waitcnt vmcnt(19)
	ds_write_b128 v169, v[124:127]
	s_waitcnt vmcnt(18)
	ds_write_b128 v169, v[128:131] offset:8192
	s_waitcnt vmcnt(17)
	ds_write_b128 v169, v[132:135] offset:16384
	s_waitcnt vmcnt(16)
	ds_write_b128 v169, v[136:139] offset:24576
	s_waitcnt vmcnt(15)
	ds_write_b128 v170, v[140:143]
	global_load_dwordx4 v[104:107], v164, s[98:99]
	global_load_dwordx4 v[108:111], v165, s[98:99]
	global_load_dwordx4 v[112:115], v166, s[98:99]
	global_load_dwordx4 v[116:119], v167, s[98:99]
	global_load_dwordx4 v[120:123], v168, s[96:97]
	s_add_u32 s98, s98, 0x100
	s_addc_u32 s99, s99, 0
	s_add_u32 s96, s96, 0x100
	s_addc_u32 s97, s97, 0
	ds_read_b128 v[204:207], v175 offset:36864
	ds_read_b128 v[208:211], v171 offset:36864
	ds_read_b128 v[212:215], v176 offset:36864
	ds_read_b128 v[216:219], v172 offset:36864
	ds_read_b128 v[220:223], v177 offset:36864
	ds_read_b128 v[224:227], v173 offset:36864
	ds_read_b128 v[228:231], v178 offset:36864
	ds_read_b128 v[232:235], v174 offset:36864
	s_waitcnt lgkmcnt(6)
	v_mfma_f32_16x16x32_bf16 v[0:3], v[204:207], v[208:211], v[0:3]
	s_waitcnt lgkmcnt(4)
	v_mfma_f32_16x16x32_bf16 v[0:3], v[212:215], v[216:219], v[0:3]
	s_waitcnt lgkmcnt(2)
	v_mfma_f32_16x16x32_bf16 v[0:3], v[220:223], v[224:227], v[0:3]
	s_waitcnt lgkmcnt(0)
	v_mfma_f32_16x16x32_bf16 v[0:3], v[228:231], v[232:235], v[0:3]
	s_waitcnt lgkmcnt(0)
	s_barrier
	s_waitcnt vmcnt(19)
	ds_write_b128 v169, v[144:147] offset:36864
	s_waitcnt vmcnt(18)
	ds_write_b128 v169, v[148:151] offset:45056
	s_waitcnt vmcnt(17)
	ds_write_b128 v169, v[152:155] offset:53248
	s_waitcnt vmcnt(16)
	ds_write_b128 v169, v[156:159] offset:61440
	s_waitcnt vmcnt(15)
	ds_write_b128 v170, v[160:163] offset:36864
	global_load_dwordx4 v[124:127], v164, s[98:99]
	global_load_dwordx4 v[128:131], v165, s[98:99]
	global_load_dwordx4 v[132:135], v166, s[98:99]
	global_load_dwordx4 v[136:139], v167, s[98:99]
	global_load_dwordx4 v[140:143], v168, s[96:97]
	s_add_u32 s98, s98, 0x100
	s_addc_u32 s99, s99, 0
	s_add_u32 s96, s96, 0x100
	s_addc_u32 s97, s97, 0
	ds_read_b128 v[204:207], v175
	ds_read_b128 v[208:211], v171
	ds_read_b128 v[212:215], v176
	ds_read_b128 v[216:219], v172
	ds_read_b128 v[220:223], v177
	ds_read_b128 v[224:227], v173
	ds_read_b128 v[228:231], v178
	ds_read_b128 v[232:235], v174
	s_waitcnt lgkmcnt(6)
	v_mfma_f32_16x16x32_bf16 v[0:3], v[204:207], v[208:211], v[0:3]
	s_waitcnt lgkmcnt(4)
	v_mfma_f32_16x16x32_bf16 v[0:3], v[212:215], v[216:219], v[0:3]
	s_waitcnt lgkmcnt(2)
	v_mfma_f32_16x16x32_bf16 v[0:3], v[220:223], v[224:227], v[0:3]
	s_waitcnt lgkmcnt(0)
	v_mfma_f32_16x16x32_bf16 v[0:3], v[228:231], v[232:235], v[0:3]
	s_waitcnt lgkmcnt(0)
	s_barrier
; template <int MODE>
; __device__ __forceinline__ void sgemm_sample(LAS unsigned char* lds, const bf16_t* A, const bf16_t* Bt, int K, const float* resid, float* out, bf16_t* xb, float* ssq_out, const float* ssq_in) {
;     ...
; #pragma unroll 8
;         for (int ks = 0; ks < K / 32; ++ks) {
;             const bf16x8 a = *(const bf16x8*)(ap + ks * 32); const bf16x8 b = *(const bf16x8*)(bp + ks * 32);
;             acc = __builtin_amdgcn_mfma_f32_16x16x32_bf16(b, a, acc, 0, 0, 0);
;         }
	s_waitcnt vmcnt(19)
	ds_write_b128 v169, v[64:67]
	s_waitcnt vmcnt(18)
	ds_write_b128 v169, v[68:71] offset:8192
	s_waitcnt vmcnt(17)
	ds_write_b128 v169, v[72:75] offset:16384
	s_waitcnt vmcnt(16)
	ds_write_b128 v169, v[76:79] offset:24576
	s_waitcnt vmcnt(15)
	ds_write_b128 v170, v[80:83]
	global_load_dwordx4 v[144:147], v164, s[98:99]
	global_load_dwordx4 v[148:151], v165, s[98:99]
	global_load_dwordx4 v[152:155], v166, s[98:99]
	global_load_dwordx4 v[156:159], v167, s[98:99]
	global_load_dwordx4 v[160:163], v168, s[96:97]
	s_add_u32 s98, s98, 0x100
	s_addc_u32 s99, s99, 0
	s_add_u32 s96, s96, 0x100
	s_addc_u32 s97, s97, 0
	ds_read_b128 v[204:207], v175 offset:36864
	ds_read_b128 v[208:211], v171 offset:36864
	ds_read_b128 v[212:215], v176 offset:36864
	ds_read_b128 v[216:219], v172 offset:36864
	ds_read_b128 v[220:223], v177 offset:36864
	ds_read_b128 v[224:227], v173 offset:36864
	ds_read_b128 v[228:231], v178 offset:36864
	ds_read_b128 v[232:235], v174 offset:36864
	s_waitcnt lgkmcnt(6)
	v_mfma_f32_16x16x32_bf16 v[0:3], v[204:207], v[208:211], v[0:3]
	s_waitcnt lgkmcnt(4)
	v_mfma_f32_16x16x32_bf16 v[0:3], v[212:215], v[216:219], v[0:3]
	s_waitcnt lgkmcnt(2)
	v_mfma_f32_16x16x32_bf16 v[0:3], v[220:223], v[224:227], v[0:3]
	s_waitcnt lgkmcnt(0)
	v_mfma_f32_16x16x32_bf16 v[0:3], v[228:231], v[232:235], v[0:3]
	s_waitcnt lgkmcnt(0)
	s_barrier
	s_waitcnt vmcnt(19)
	ds_write_b128 v169, v[84:87] offset:36864
	s_waitcnt vmcnt(18)
	ds_write_b128 v169, v[88:91] offset:45056
	s_waitcnt vmcnt(17)
	ds_write_b128 v169, v[92:95] offset:53248
	s_waitcnt vmcnt(16)
	ds_write_b128 v169, v[96:99] offset:61440
	s_waitcnt vmcnt(15)
	ds_write_b128 v170, v[100:103] offset:36864
	global_load_dwordx4 v[64:67], v164, s[98:99]
	global_load_dwordx4 v[68:71], v165, s[98:99]
	global_load_dwordx4 v[72:75], v166, s[98:99]
	global_load_dwordx4 v[76:79], v167, s[98:99]
	global_load_dwordx4 v[80:83], v168, s[96:97]
	s_add_u32 s98, s98, 0x100
	s_addc_u32 s99, s99, 0
	s_add_u32 s96, s96, 0x100
	s_addc_u32 s97, s97, 0
	ds_read_b128 v[204:207], v175
	ds_read_b128 v[208:211], v171
	ds_read_b128 v[212:215], v176
	ds_read_b128 v[216:219], v172
	ds_read_b128 v[220:223], v177
	ds_read_b128 v[224:227], v173
	ds_read_b128 v[228:231], v178
	ds_read_b128 v[232:235], v174
	s_waitcnt lgkmcnt(6)
	v_mfma_f32_16x16x32_bf16 v[0:3], v[204:207], v[208:211], v[0:3]
	s_waitcnt lgkmcnt(4)
	v_mfma_f32_16x16x32_bf16 v[0:3], v[212:215], v[216:219], v[0:3]
	s_waitcnt lgkmcnt(2)
	v_mfma_f32_16x16x32_bf16 v[0:3], v[220:223], v[224:227], v[0:3]
	s_waitcnt lgkmcnt(0)
	v_mfma_f32_16x16x32_bf16 v[0:3], v[228:231], v[232:235], v[0:3]
	s_waitcnt lgkmcnt(0)
	s_barrier
	s_waitcnt vmcnt(19)
	ds_write_b128 v169, v[104:107]
	s_waitcnt vmcnt(18)
	ds_write_b128 v169, v[108:111] offset:8192
	s_waitcnt vmcnt(17)
	ds_write_b128 v169, v[112:115] offset:16384
	s_waitcnt vmcnt(16)
	ds_write_b128 v169, v[116:119] offset:24576
	s_waitcnt vmcnt(15)
	ds_write_b128 v170, v[120:123]
	global_load_dwordx4 v[84:87], v164, s[98:99]
	global_load_dwordx4 v[88:91], v165, s[98:99]
	global_load_dwordx4 v[92:95], v166, s[98:99]
	global_load_dwordx4 v[96:99], v167, s[98:99]
	global_load_dwordx4 v[100:103], v168, s[96:97]
	s_add_u32 s98, s98, 0x100
	s_addc_u32 s99, s99, 0
	s_add_u32 s96, s96, 0x100
	s_addc_u32 s97, s97, 0
	ds_read_b128 v[204:207], v175 offset:36864
	ds_read_b128 v[208:211], v171 offset:36864
	ds_read_b128 v[212:215], v176 offset:36864
	ds_read_b128 v[216:219], v172 offset:36864
	ds_read_b128 v[220:223], v177 offset:36864
	ds_read_b128 v[224:227], v173 offset:36864
	ds_read_b128 v[228:231], v178 offset:36864
	ds_read_b128 v[232:235], v174 offset:36864
	s_waitcnt lgkmcnt(6)
	v_mfma_f32_16x16x32_bf16 v[0:3], v[204:207], v[208:211], v[0:3]
	s_waitcnt lgkmcnt(4)
	v_mfma_f32_16x16x32_bf16 v[0:3], v[212:215], v[216:219], v[0:3]
	s_waitcnt lgkmcnt(2)
	v_mfma_f32_16x16x32_bf16 v[0:3], v[220:223], v[224:227], v[0:3]
	s_waitcnt lgkmcnt(0)
	v_mfma_f32_16x16x32_bf16 v[0:3], v[228:231], v[232:235], v[0:3]
	s_waitcnt lgkmcnt(0)
	s_barrier
	s_waitcnt vmcnt(19)
	ds_write_b128 v169, v[124:127] offset:36864
	s_waitcnt vmcnt(18)
	ds_write_b128 v169, v[128:131] offset:45056
	s_waitcnt vmcnt(17)
	ds_write_b128 v169, v[132:135] offset:53248
	s_waitcnt vmcnt(16)
	ds_write_b128 v169, v[136:139] offset:61440
	s_waitcnt vmcnt(15)
	ds_write_b128 v170, v[140:143] offset:36864
	global_load_dwordx4 v[104:107], v164, s[98:99]
	global_load_dwordx4 v[108:111], v165, s[98:99]
	global_load_dwordx4 v[112:115], v166, s[98:99]
	global_load_dwordx4 v[116:119], v167, s[98:99]
	global_load_dwordx4 v[120:123], v168, s[96:97]
	s_add_u32 s98, s98, 0x100
	s_addc_u32 s99, s99, 0
	s_add_u32 s96, s96, 0x100
	s_addc_u32 s97, s97, 0
	ds_read_b128 v[204:207], v175
	ds_read_b128 v[208:211], v171
	ds_read_b128 v[212:215], v176
	ds_read_b128 v[216:219], v172
	ds_read_b128 v[220:223], v177
	ds_read_b128 v[224:227], v173
	ds_read_b128 v[228:231], v178
	ds_read_b128 v[232:235], v174
	s_waitcnt lgkmcnt(6)
	v_mfma_f32_16x16x32_bf16 v[0:3], v[204:207], v[208:211], v[0:3]
	s_waitcnt lgkmcnt(4)
	v_mfma_f32_16x16x32_bf16 v[0:3], v[212:215], v[216:219], v[0:3]
	s_waitcnt lgkmcnt(2)
	v_mfma_f32_16x16x32_bf16 v[0:3], v[220:223], v[224:227], v[0:3]
	s_waitcnt lgkmcnt(0)
	v_mfma_f32_16x16x32_bf16 v[0:3], v[228:231], v[232:235], v[0:3]
	s_waitcnt lgkmcnt(0)
	s_barrier
; template <int MODE>
; __device__ __forceinline__ void sgemm_sample(LAS unsigned char* lds, const bf16_t* A, const bf16_t* Bt, int K, const float* resid, float* out, bf16_t* xb, float* ssq_out, const float* ssq_in) {
;     ...
; #pragma unroll 8
;         for (int ks = 0; ks < K / 32; ++ks) {
;             const bf16x8 a = *(const bf16x8*)(ap + ks * 32); const bf16x8 b = *(const bf16x8*)(bp + ks * 32);
;             acc = __builtin_amdgcn_mfma_f32_16x16x32_bf16(b, a, acc, 0, 0, 0);
;         }
	s_waitcnt vmcnt(19)
	ds_write_b128 v169, v[144:147]
	s_waitcnt vmcnt(18)
	ds_write_b128 v169, v[148:151] offset:8192
	s_waitcnt vmcnt(17)
	ds_write_b128 v169, v[152:155] offset:16384
	s_waitcnt vmcnt(16)
	ds_write_b128 v169, v[156:159] offset:24576
	s_waitcnt vmcnt(15)
	ds_write_b128 v170, v[160:163]
	global_load_dwordx4 v[124:127], v164, s[98:99]
	global_load_dwordx4 v[128:131], v165, s[98:99]
	global_load_dwordx4 v[132:135], v166, s[98:99]
	global_load_dwordx4 v[136:139], v167, s[98:99]
	global_load_dwordx4 v[140:143], v168, s[96:97]
	s_add_u32 s98, s98, 0x100
	s_addc_u32 s99, s99, 0
	s_add_u32 s96, s96, 0x100
	s_addc_u32 s97, s97, 0
	ds_read_b128 v[204:207], v175 offset:36864
	ds_read_b128 v[208:211], v171 offset:36864
	ds_read_b128 v[212:215], v176 offset:36864
	ds_read_b128 v[216:219], v172 offset:36864
	ds_read_b128 v[220:223], v177 offset:36864
	ds_read_b128 v[224:227], v173 offset:36864
	ds_read_b128 v[228:231], v178 offset:36864
	ds_read_b128 v[232:235], v174 offset:36864
	s_waitcnt lgkmcnt(6)
	v_mfma_f32_16x16x32_bf16 v[0:3], v[204:207], v[208:211], v[0:3]
	s_waitcnt lgkmcnt(4)
	v_mfma_f32_16x16x32_bf16 v[0:3], v[212:215], v[216:219], v[0:3]
	s_waitcnt lgkmcnt(2)
	v_mfma_f32_16x16x32_bf16 v[0:3], v[220:223], v[224:227], v[0:3]
	s_waitcnt lgkmcnt(0)
	v_mfma_f32_16x16x32_bf16 v[0:3], v[228:231], v[232:235], v[0:3]
	s_waitcnt lgkmcnt(0)
	s_barrier
	s_waitcnt vmcnt(19)
	ds_write_b128 v169, v[64:67] offset:36864
	s_waitcnt vmcnt(18)
	ds_write_b128 v169, v[68:71] offset:45056
	s_waitcnt vmcnt(17)
	ds_write_b128 v169, v[72:75] offset:53248
	s_waitcnt vmcnt(16)
	ds_write_b128 v169, v[76:79] offset:61440
	s_waitcnt vmcnt(15)
	ds_write_b128 v170, v[80:83] offset:36864
	global_load_dwordx4 v[144:147], v164, s[98:99]
	global_load_dwordx4 v[148:151], v165, s[98:99]
	global_load_dwordx4 v[152:155], v166, s[98:99]
	global_load_dwordx4 v[156:159], v167, s[98:99]
	global_load_dwordx4 v[160:163], v168, s[96:97]
	s_add_u32 s98, s98, 0x100
	s_addc_u32 s99, s99, 0
	s_add_u32 s96, s96, 0x100
	s_addc_u32 s97, s97, 0
	ds_read_b128 v[204:207], v175
	ds_read_b128 v[208:211], v171
	ds_read_b128 v[212:215], v176
	ds_read_b128 v[216:219], v172
	ds_read_b128 v[220:223], v177
	ds_read_b128 v[224:227], v173
	ds_read_b128 v[228:231], v178
	ds_read_b128 v[232:235], v174
	s_waitcnt lgkmcnt(6)
	v_mfma_f32_16x16x32_bf16 v[0:3], v[204:207], v[208:211], v[0:3]
	s_waitcnt lgkmcnt(4)
	v_mfma_f32_16x16x32_bf16 v[0:3], v[212:215], v[216:219], v[0:3]
	s_waitcnt lgkmcnt(2)
	v_mfma_f32_16x16x32_bf16 v[0:3], v[220:223], v[224:227], v[0:3]
	s_waitcnt lgkmcnt(0)
	v_mfma_f32_16x16x32_bf16 v[0:3], v[228:231], v[232:235], v[0:3]
	s_waitcnt lgkmcnt(0)
	s_barrier
	s_waitcnt vmcnt(19)
	ds_write_b128 v169, v[84:87]
	s_waitcnt vmcnt(18)
	ds_write_b128 v169, v[88:91] offset:8192
	s_waitcnt vmcnt(17)
	ds_write_b128 v169, v[92:95] offset:16384
	s_waitcnt vmcnt(16)
	ds_write_b128 v169, v[96:99] offset:24576
	s_waitcnt vmcnt(15)
	ds_write_b128 v170, v[100:103]
	global_load_dwordx4 v[64:67], v164, s[98:99]
	global_load_dwordx4 v[68:71], v165, s[98:99]
	global_load_dwordx4 v[72:75], v166, s[98:99]
	global_load_dwordx4 v[76:79], v167, s[98:99]
	global_load_dwordx4 v[80:83], v168, s[96:97]
	s_add_u32 s98, s98, 0x100
	s_addc_u32 s99, s99, 0
	s_add_u32 s96, s96, 0x100
	s_addc_u32 s97, s97, 0
	ds_read_b128 v[204:207], v175 offset:36864
	ds_read_b128 v[208:211], v171 offset:36864
	ds_read_b128 v[212:215], v176 offset:36864
	ds_read_b128 v[216:219], v172 offset:36864
	ds_read_b128 v[220:223], v177 offset:36864
	ds_read_b128 v[224:227], v173 offset:36864
	ds_read_b128 v[228:231], v178 offset:36864
	ds_read_b128 v[232:235], v174 offset:36864
	s_waitcnt lgkmcnt(6)
	v_mfma_f32_16x16x32_bf16 v[0:3], v[204:207], v[208:211], v[0:3]
	s_waitcnt lgkmcnt(4)
	v_mfma_f32_16x16x32_bf16 v[0:3], v[212:215], v[216:219], v[0:3]
	s_waitcnt lgkmcnt(2)
	v_mfma_f32_16x16x32_bf16 v[0:3], v[220:223], v[224:227], v[0:3]
	s_waitcnt lgkmcnt(0)
	v_mfma_f32_16x16x32_bf16 v[0:3], v[228:231], v[232:235], v[0:3]
	s_waitcnt lgkmcnt(0)
	s_barrier
	s_waitcnt vmcnt(19)
	ds_write_b128 v169, v[104:107] offset:36864
	s_waitcnt vmcnt(18)
	ds_write_b128 v169, v[108:111] offset:45056
	s_waitcnt vmcnt(17)
	ds_write_b128 v169, v[112:115] offset:53248
	s_waitcnt vmcnt(16)
	ds_write_b128 v169, v[116:119] offset:61440
	s_waitcnt vmcnt(15)
	ds_write_b128 v170, v[120:123] offset:36864
	global_load_dwordx4 v[84:87], v164, s[98:99]
	global_load_dwordx4 v[88:91], v165, s[98:99]
	global_load_dwordx4 v[92:95], v166, s[98:99]
	global_load_dwordx4 v[96:99], v167, s[98:99]
	global_load_dwordx4 v[100:103], v168, s[96:97]
	s_add_u32 s98, s98, 0x100
	s_addc_u32 s99, s99, 0
	s_add_u32 s96, s96, 0x100
	s_addc_u32 s97, s97, 0
	ds_read_b128 v[204:207], v175
	ds_read_b128 v[208:211], v171
	ds_read_b128 v[212:215], v176
	ds_read_b128 v[216:219], v172
	ds_read_b128 v[220:223], v177
	ds_read_b128 v[224:227], v173
	ds_read_b128 v[228:231], v178
	ds_read_b128 v[232:235], v174
	s_waitcnt lgkmcnt(6)
	v_mfma_f32_16x16x32_bf16 v[0:3], v[204:207], v[208:211], v[0:3]
	s_waitcnt lgkmcnt(4)
	v_mfma_f32_16x16x32_bf16 v[0:3], v[212:215], v[216:219], v[0:3]
	s_waitcnt lgkmcnt(2)
	v_mfma_f32_16x16x32_bf16 v[0:3], v[220:223], v[224:227], v[0:3]
	s_waitcnt lgkmcnt(0)
	v_mfma_f32_16x16x32_bf16 v[0:3], v[228:231], v[232:235], v[0:3]
	s_waitcnt lgkmcnt(0)
	s_barrier
; template <int MODE>
; __device__ __forceinline__ void sgemm_sample(LAS unsigned char* lds, const bf16_t* A, const bf16_t* Bt, int K, const float* resid, float* out, bf16_t* xb, float* ssq_out, const float* ssq_in) {
;     ...
; #pragma unroll 8
;         for (int ks = 0; ks < K / 32; ++ks) {
;             const bf16x8 a = *(const bf16x8*)(ap + ks * 32); const bf16x8 b = *(const bf16x8*)(bp + ks * 32);
;             acc = __builtin_amdgcn_mfma_f32_16x16x32_bf16(b, a, acc, 0, 0, 0);
;         }
	s_waitcnt vmcnt(19)
	ds_write_b128 v169, v[124:127]
	s_waitcnt vmcnt(18)
	ds_write_b128 v169, v[128:131] offset:8192
	s_waitcnt vmcnt(17)
	ds_write_b128 v169, v[132:135] offset:16384
	s_waitcnt vmcnt(16)
	ds_write_b128 v169, v[136:139] offset:24576
	s_waitcnt vmcnt(15)
	ds_write_b128 v170, v[140:143]
	ds_read_b128 v[204:207], v175 offset:36864
	ds_read_b128 v[208:211], v171 offset:36864
	ds_read_b128 v[212:215], v176 offset:36864
	ds_read_b128 v[216:219], v172 offset:36864
	ds_read_b128 v[220:223], v177 offset:36864
	ds_read_b128 v[224:227], v173 offset:36864
	ds_read_b128 v[228:231], v178 offset:36864
	ds_read_b128 v[232:235], v174 offset:36864
	s_waitcnt lgkmcnt(6)
	v_mfma_f32_16x16x32_bf16 v[0:3], v[204:207], v[208:211], v[0:3]
	s_waitcnt lgkmcnt(4)
	v_mfma_f32_16x16x32_bf16 v[0:3], v[212:215], v[216:219], v[0:3]
	s_waitcnt lgkmcnt(2)
	v_mfma_f32_16x16x32_bf16 v[0:3], v[220:223], v[224:227], v[0:3]
	s_waitcnt lgkmcnt(0)
	v_mfma_f32_16x16x32_bf16 v[0:3], v[228:231], v[232:235], v[0:3]
	s_waitcnt lgkmcnt(0)
	s_barrier
	s_waitcnt vmcnt(14)
	ds_write_b128 v169, v[144:147] offset:36864
	s_waitcnt vmcnt(13)
	ds_write_b128 v169, v[148:151] offset:45056
	s_waitcnt vmcnt(12)
	ds_write_b128 v169, v[152:155] offset:53248
	s_waitcnt vmcnt(11)
	ds_write_b128 v169, v[156:159] offset:61440
	s_waitcnt vmcnt(10)
	ds_write_b128 v170, v[160:163] offset:36864
	ds_read_b128 v[204:207], v175
	ds_read_b128 v[208:211], v171
	ds_read_b128 v[212:215], v176
	ds_read_b128 v[216:219], v172
	ds_read_b128 v[220:223], v177
	ds_read_b128 v[224:227], v173
	ds_read_b128 v[228:231], v178
	ds_read_b128 v[232:235], v174
	s_waitcnt lgkmcnt(6)
	v_mfma_f32_16x16x32_bf16 v[0:3], v[204:207], v[208:211], v[0:3]
	s_waitcnt lgkmcnt(4)
	v_mfma_f32_16x16x32_bf16 v[0:3], v[212:215], v[216:219], v[0:3]
	s_waitcnt lgkmcnt(2)
	v_mfma_f32_16x16x32_bf16 v[0:3], v[220:223], v[224:227], v[0:3]
	s_waitcnt lgkmcnt(0)
	v_mfma_f32_16x16x32_bf16 v[0:3], v[228:231], v[232:235], v[0:3]
	s_waitcnt lgkmcnt(0)
	s_barrier
	s_waitcnt vmcnt(9)
	ds_write_b128 v169, v[64:67]
	s_waitcnt vmcnt(8)
	ds_write_b128 v169, v[68:71] offset:8192
	s_waitcnt vmcnt(7)
	ds_write_b128 v169, v[72:75] offset:16384
	s_waitcnt vmcnt(6)
	ds_write_b128 v169, v[76:79] offset:24576
	s_waitcnt vmcnt(5)
	ds_write_b128 v170, v[80:83]
	ds_read_b128 v[204:207], v175 offset:36864
	ds_read_b128 v[208:211], v171 offset:36864
	ds_read_b128 v[212:215], v176 offset:36864
	ds_read_b128 v[216:219], v172 offset:36864
	ds_read_b128 v[220:223], v177 offset:36864
	ds_read_b128 v[224:227], v173 offset:36864
	ds_read_b128 v[228:231], v178 offset:36864
	ds_read_b128 v[232:235], v174 offset:36864
	s_waitcnt lgkmcnt(6)
	v_mfma_f32_16x16x32_bf16 v[0:3], v[204:207], v[208:211], v[0:3]
	s_waitcnt lgkmcnt(4)
	v_mfma_f32_16x16x32_bf16 v[0:3], v[212:215], v[216:219], v[0:3]
	s_waitcnt lgkmcnt(2)
	v_mfma_f32_16x16x32_bf16 v[0:3], v[220:223], v[224:227], v[0:3]
	s_waitcnt lgkmcnt(0)
	v_mfma_f32_16x16x32_bf16 v[0:3], v[228:231], v[232:235], v[0:3]
	s_waitcnt lgkmcnt(0)
	s_barrier
	s_waitcnt vmcnt(4)
	ds_write_b128 v169, v[84:87] offset:36864
	s_waitcnt vmcnt(3)
	ds_write_b128 v169, v[88:91] offset:45056
	s_waitcnt vmcnt(2)
	ds_write_b128 v169, v[92:95] offset:53248
	s_waitcnt vmcnt(1)
	ds_write_b128 v169, v[96:99] offset:61440
	s_waitcnt vmcnt(0)
	ds_write_b128 v170, v[100:103] offset:36864
	ds_read_b128 v[204:207], v175
	ds_read_b128 v[208:211], v171
	ds_read_b128 v[212:215], v176
	ds_read_b128 v[216:219], v172
	ds_read_b128 v[220:223], v177
	ds_read_b128 v[224:227], v173
	ds_read_b128 v[228:231], v178
	ds_read_b128 v[232:235], v174
	s_waitcnt lgkmcnt(6)
	v_mfma_f32_16x16x32_bf16 v[0:3], v[204:207], v[208:211], v[0:3]
	s_waitcnt lgkmcnt(4)
	v_mfma_f32_16x16x32_bf16 v[0:3], v[212:215], v[216:219], v[0:3]
	s_waitcnt lgkmcnt(2)
	v_mfma_f32_16x16x32_bf16 v[0:3], v[220:223], v[224:227], v[0:3]
	s_waitcnt lgkmcnt(0)
	v_mfma_f32_16x16x32_bf16 v[0:3], v[228:231], v[232:235], v[0:3]
	s_waitcnt lgkmcnt(0)
	s_barrier
	ds_read_b128 v[204:207], v175 offset:36864
	ds_read_b128 v[208:211], v171 offset:36864
	ds_read_b128 v[212:215], v176 offset:36864
	ds_read_b128 v[216:219], v172 offset:36864
	ds_read_b128 v[220:223], v177 offset:36864
	ds_read_b128 v[224:227], v173 offset:36864
	ds_read_b128 v[228:231], v178 offset:36864
	ds_read_b128 v[232:235], v174 offset:36864
	s_waitcnt lgkmcnt(6)
	v_mfma_f32_16x16x32_bf16 v[0:3], v[204:207], v[208:211], v[0:3]
	s_waitcnt lgkmcnt(4)
	v_mfma_f32_16x16x32_bf16 v[0:3], v[212:215], v[216:219], v[0:3]
	s_waitcnt lgkmcnt(2)
	v_mfma_f32_16x16x32_bf16 v[0:3], v[220:223], v[224:227], v[0:3]
	s_waitcnt lgkmcnt(0)
	v_mfma_f32_16x16x32_bf16 v[0:3], v[228:231], v[232:235], v[0:3]
	s_nop 7
	s_nop 7
	s_nop 3
	s_branch .Lsgx3_done
